# batched the serialized conv-tap loads (lru/ssd stage loops, local+out phases): 8 masked loads in flight per trip instead of load-wait per tap
# speedup vs baseline: 1.3348x; 1.0236x over previous
.LBB0_325:
	v_add_u32_e32 v66, s19, v64
	v_mov_b32_e32 v76, 0
	v_mov_b32_e32 v77, 0
	v_mov_b32_e32 v78, 0
	v_mov_b32_e32 v79, 0
	v_add_u32_e32 v108, 30, v66
	v_cmp_gt_u32_e32 vcc, s18, v108
	s_and_saveexec_b64 s[4:5], vcc
	s_cbranch_execz .Lcv0_0
	v_lshl_add_u64 v[76:77], v[58:59], 0, v[128:129]
	v_add_co_u32_e32 v76, vcc, 0x3195000, v76
	s_nop 1
	v_addc_co_u32_e32 v77, vcc, 0, v77, vcc
	global_load_dwordx4 v[76:79], v[76:77], off offset:1600
.Lcv0_0:
	s_or_b64 exec, exec, s[4:5]
	v_mov_b32_e32 v80, 0
	v_mov_b32_e32 v81, 0
	v_mov_b32_e32 v82, 0
	v_mov_b32_e32 v83, 0
	v_add_u32_e32 v108, 31, v66
	v_cmp_gt_u32_e32 vcc, s18, v108
	s_and_saveexec_b64 s[4:5], vcc
	s_cbranch_execz .Lcv0_1
	v_lshl_add_u64 v[80:81], v[62:63], 0, v[128:129]
	v_add_co_u32_e32 v80, vcc, 0x3195000, v80
	s_nop 1
	v_addc_co_u32_e32 v81, vcc, 0, v81, vcc
	global_load_dwordx4 v[80:83], v[80:81], off offset:1600
.Lcv0_1:
	s_or_b64 exec, exec, s[4:5]
	v_mov_b32_e32 v84, 0
	v_mov_b32_e32 v85, 0
	v_mov_b32_e32 v86, 0
	v_mov_b32_e32 v87, 0
	v_add_u32_e32 v108, 32, v66
	v_cmp_gt_u32_e32 vcc, s18, v108
	s_and_saveexec_b64 s[4:5], vcc
	s_cbranch_execz .Lcv0_2
	v_lshl_add_u64 v[84:85], v[56:57], 0, v[128:129]
	v_add_co_u32_e32 v84, vcc, 0x3195000, v84
	s_nop 1
	v_addc_co_u32_e32 v85, vcc, 0, v85, vcc
	global_load_dwordx4 v[84:87], v[84:85], off offset:1600
.Lcv0_2:
	s_or_b64 exec, exec, s[4:5]
	v_mov_b32_e32 v88, 0
	v_mov_b32_e32 v89, 0
	v_mov_b32_e32 v90, 0
	v_mov_b32_e32 v91, 0
	v_add_u32_e32 v108, 33, v66
	v_cmp_gt_u32_e32 vcc, s18, v108
	s_and_saveexec_b64 s[4:5], vcc
	s_cbranch_execz .Lcv0_3
	v_lshl_add_u64 v[88:89], v[60:61], 0, v[128:129]
	v_add_co_u32_e32 v88, vcc, 0x3195000, v88
	s_nop 1
	v_addc_co_u32_e32 v89, vcc, 0, v89, vcc
	global_load_dwordx4 v[88:91], v[88:89], off offset:1600
.Lcv0_3:
	s_or_b64 exec, exec, s[4:5]
	v_mov_b32_e32 v92, 0
	v_mov_b32_e32 v93, 0
	v_mov_b32_e32 v94, 0
	v_mov_b32_e32 v95, 0
	v_add_u32_e32 v108, 46, v66
	v_cmp_gt_u32_e32 vcc, s18, v108
	s_and_saveexec_b64 s[4:5], vcc
	s_cbranch_execz .Lcv0_4
	v_lshl_add_u64 v[92:93], v[54:55], 0, v[128:129]
	v_add_co_u32_e32 v92, vcc, 0x3195000, v92
	s_nop 1
	v_addc_co_u32_e32 v93, vcc, 0, v93, vcc
	global_load_dwordx4 v[92:95], v[92:93], off offset:1600
.Lcv0_4:
	s_or_b64 exec, exec, s[4:5]
	v_mov_b32_e32 v96, 0
	v_mov_b32_e32 v97, 0
	v_mov_b32_e32 v98, 0
	v_mov_b32_e32 v99, 0
	v_add_u32_e32 v108, 47, v66
	v_cmp_gt_u32_e32 vcc, s18, v108
	s_and_saveexec_b64 s[4:5], vcc
	s_cbranch_execz .Lcv0_5
	v_lshl_add_u64 v[96:97], v[52:53], 0, v[128:129]
	v_add_co_u32_e32 v96, vcc, 0x3195000, v96
	s_nop 1
	v_addc_co_u32_e32 v97, vcc, 0, v97, vcc
	global_load_dwordx4 v[96:99], v[96:97], off offset:1600
.Lcv0_5:
	s_or_b64 exec, exec, s[4:5]
	v_mov_b32_e32 v100, 0
	v_mov_b32_e32 v101, 0
	v_mov_b32_e32 v102, 0
	v_mov_b32_e32 v103, 0
	v_add_u32_e32 v108, 48, v66
	v_cmp_gt_u32_e32 vcc, s18, v108
	s_and_saveexec_b64 s[4:5], vcc
	s_cbranch_execz .Lcv0_6
	v_lshl_add_u64 v[100:101], v[48:49], 0, v[128:129]
	v_add_co_u32_e32 v100, vcc, 0x3195000, v100
	s_nop 1
	v_addc_co_u32_e32 v101, vcc, 0, v101, vcc
	global_load_dwordx4 v[100:103], v[100:101], off offset:1600
.Lcv0_6:
	s_or_b64 exec, exec, s[4:5]
	v_mov_b32_e32 v104, 0
	v_mov_b32_e32 v105, 0
	v_mov_b32_e32 v106, 0
	v_mov_b32_e32 v107, 0
	v_add_u32_e32 v108, 49, v66
	v_cmp_gt_u32_e32 vcc, s18, v108
	s_and_saveexec_b64 s[4:5], vcc
	s_cbranch_execz .Lcv0_7
	v_lshl_add_u64 v[104:105], v[50:51], 0, v[128:129]
	v_add_co_u32_e32 v104, vcc, 0x3195000, v104
	s_nop 1
	v_addc_co_u32_e32 v105, vcc, 0, v105, vcc
	global_load_dwordx4 v[104:107], v[104:105], off offset:1600
.Lcv0_7:
	s_or_b64 exec, exec, s[4:5]
	s_waitcnt vmcnt(0)
	s_waitcnt vmcnt(8)
	v_mov_b64_e32 v[14:15], v[6:7]
	v_mov_b64_e32 v[12:13], v[4:5]
	v_mov_b64_e32 v[10:11], v[2:3]
	v_mov_b64_e32 v[8:9], v[0:1]
	v_mov_b32_e32 v8, v76
	v_mov_b32_e32 v9, v77
	v_mov_b32_e32 v10, v78
	v_mov_b32_e32 v11, v79
	v_lshlrev_b32_e32 v68, 16, v8
	v_and_b32_e32 v69, 0xffff0000, v8
	v_lshlrev_b32_e32 v8, 16, v9
	v_and_b32_e32 v9, 0xffff0000, v9
	v_lshlrev_b32_e32 v12, 16, v10
	v_and_b32_e32 v13, 0xffff0000, v10
	v_lshlrev_b32_e32 v10, 16, v11
	v_and_b32_e32 v11, 0xffff0000, v11
	v_pk_fma_f32 v[14:15], v[18:19], v[10:11], v[6:7]
	v_pk_fma_f32 v[12:13], v[16:17], v[12:13], v[4:5]
	v_pk_fma_f32 v[10:11], v[22:23], v[8:9], v[2:3]
	v_pk_fma_f32 v[8:9], v[20:21], v[68:69], v[0:1]
	v_mov_b32_e32 v68, v80
	v_mov_b32_e32 v69, v81
	v_mov_b32_e32 v70, v82
	v_mov_b32_e32 v71, v83
	v_lshlrev_b32_e32 v72, 16, v68
	v_and_b32_e32 v73, 0xffff0000, v68
	v_lshlrev_b32_e32 v68, 16, v69
	v_and_b32_e32 v69, 0xffff0000, v69
	v_lshlrev_b32_e32 v74, 16, v70
	v_and_b32_e32 v75, 0xffff0000, v70
	v_lshlrev_b32_e32 v70, 16, v71
	v_and_b32_e32 v71, 0xffff0000, v71
	v_pk_fma_f32 v[14:15], v[26:27], v[70:71], v[14:15]
	v_pk_fma_f32 v[12:13], v[24:25], v[74:75], v[12:13]
	v_pk_fma_f32 v[10:11], v[30:31], v[68:69], v[10:11]
	v_pk_fma_f32 v[8:9], v[28:29], v[72:73], v[8:9]
	v_mov_b32_e32 v68, v84
	v_mov_b32_e32 v69, v85
	v_mov_b32_e32 v70, v86
	v_mov_b32_e32 v71, v87
	v_lshlrev_b32_e32 v72, 16, v68
	v_and_b32_e32 v73, 0xffff0000, v68
	v_lshlrev_b32_e32 v68, 16, v69
	v_and_b32_e32 v69, 0xffff0000, v69
	v_lshlrev_b32_e32 v74, 16, v70
	v_and_b32_e32 v75, 0xffff0000, v70
	v_lshlrev_b32_e32 v70, 16, v71
	v_and_b32_e32 v71, 0xffff0000, v71
	v_pk_fma_f32 v[14:15], v[34:35], v[70:71], v[14:15]
	v_pk_fma_f32 v[12:13], v[32:33], v[74:75], v[12:13]
	v_pk_fma_f32 v[10:11], v[38:39], v[68:69], v[10:11]
	v_pk_fma_f32 v[8:9], v[36:37], v[72:73], v[8:9]
	v_mov_b32_e32 v68, v88
	v_mov_b32_e32 v69, v89
	v_mov_b32_e32 v70, v90
	v_mov_b32_e32 v71, v91
	v_lshlrev_b32_e32 v72, 16, v68
	v_and_b32_e32 v73, 0xffff0000, v68
	v_lshlrev_b32_e32 v68, 16, v69
	v_and_b32_e32 v69, 0xffff0000, v69
	v_lshlrev_b32_e32 v74, 16, v70
	v_and_b32_e32 v75, 0xffff0000, v70
	v_lshlrev_b32_e32 v70, 16, v71
	v_and_b32_e32 v71, 0xffff0000, v71
	v_pk_fma_f32 v[14:15], v[42:43], v[70:71], v[14:15]
	v_pk_fma_f32 v[12:13], v[40:41], v[74:75], v[12:13]
	v_pk_fma_f32 v[10:11], v[46:47], v[68:69], v[10:11]
	v_pk_fma_f32 v[8:9], v[44:45], v[72:73], v[8:9]
	v_cvt_pk_bf16_f32 v8, v8, v9
	v_cvt_pk_bf16_f32 v9, v10, v11
	v_cvt_pk_bf16_f32 v10, v12, v13
	v_cvt_pk_bf16_f32 v11, v14, v15
	ds_write_b128 v65, v[8:11]
	v_mov_b64_e32 v[14:15], v[6:7]
	v_mov_b64_e32 v[12:13], v[4:5]
	v_mov_b64_e32 v[10:11], v[2:3]
	v_mov_b64_e32 v[8:9], v[0:1]
	v_mov_b32_e32 v8, v92
	v_mov_b32_e32 v9, v93
	v_mov_b32_e32 v10, v94
	v_mov_b32_e32 v11, v95
	v_lshlrev_b32_e32 v68, 16, v8
	v_and_b32_e32 v69, 0xffff0000, v8
	v_lshlrev_b32_e32 v8, 16, v9
	v_and_b32_e32 v9, 0xffff0000, v9
	v_lshlrev_b32_e32 v12, 16, v10
	v_and_b32_e32 v13, 0xffff0000, v10
	v_lshlrev_b32_e32 v10, 16, v11
	v_and_b32_e32 v11, 0xffff0000, v11
	v_pk_fma_f32 v[14:15], v[18:19], v[10:11], v[6:7]
	v_pk_fma_f32 v[12:13], v[16:17], v[12:13], v[4:5]
	v_pk_fma_f32 v[10:11], v[22:23], v[8:9], v[2:3]
	v_pk_fma_f32 v[8:9], v[20:21], v[68:69], v[0:1]
	v_mov_b32_e32 v68, v96
	v_mov_b32_e32 v69, v97
	v_mov_b32_e32 v70, v98
	v_mov_b32_e32 v71, v99
	v_lshlrev_b32_e32 v72, 16, v68
	v_and_b32_e32 v73, 0xffff0000, v68
	v_lshlrev_b32_e32 v68, 16, v69
	v_and_b32_e32 v69, 0xffff0000, v69
	v_lshlrev_b32_e32 v74, 16, v70
	v_and_b32_e32 v75, 0xffff0000, v70
	v_lshlrev_b32_e32 v70, 16, v71
	v_and_b32_e32 v71, 0xffff0000, v71
	v_pk_fma_f32 v[14:15], v[26:27], v[70:71], v[14:15]
	v_pk_fma_f32 v[12:13], v[24:25], v[74:75], v[12:13]
	v_pk_fma_f32 v[10:11], v[30:31], v[68:69], v[10:11]
	v_pk_fma_f32 v[8:9], v[28:29], v[72:73], v[8:9]
	v_mov_b32_e32 v68, v100
	v_mov_b32_e32 v69, v101
	v_mov_b32_e32 v70, v102
	v_mov_b32_e32 v71, v103
	v_lshlrev_b32_e32 v72, 16, v68
	v_and_b32_e32 v73, 0xffff0000, v68
	v_lshlrev_b32_e32 v68, 16, v69
	v_and_b32_e32 v69, 0xffff0000, v69
	v_lshlrev_b32_e32 v74, 16, v70
	v_and_b32_e32 v75, 0xffff0000, v70
	v_lshlrev_b32_e32 v70, 16, v71
	v_and_b32_e32 v71, 0xffff0000, v71
	v_pk_fma_f32 v[14:15], v[34:35], v[70:71], v[14:15]
	v_pk_fma_f32 v[12:13], v[32:33], v[74:75], v[12:13]
	v_pk_fma_f32 v[10:11], v[38:39], v[68:69], v[10:11]
	v_pk_fma_f32 v[8:9], v[36:37], v[72:73], v[8:9]
	v_mov_b32_e32 v66, v104
	v_mov_b32_e32 v67, v105
	v_mov_b32_e32 v68, v106
	v_mov_b32_e32 v69, v107
	v_lshlrev_b32_e32 v70, 16, v66
	v_and_b32_e32 v71, 0xffff0000, v66
	v_lshlrev_b32_e32 v66, 16, v67
	v_and_b32_e32 v67, 0xffff0000, v67
	v_lshlrev_b32_e32 v72, 16, v68
	v_and_b32_e32 v73, 0xffff0000, v68
	v_lshlrev_b32_e32 v68, 16, v69
	v_and_b32_e32 v69, 0xffff0000, v69
	v_pk_fma_f32 v[14:15], v[42:43], v[68:69], v[14:15]
	v_pk_fma_f32 v[12:13], v[40:41], v[72:73], v[12:13]
	v_pk_fma_f32 v[10:11], v[46:47], v[66:67], v[10:11]
	v_pk_fma_f32 v[8:9], v[44:45], v[70:71], v[8:9]
	s_branch .LBB0_324

.LBB0_497:
	v_add_u32_e32 v70, s25, v68
	v_mov_b32_e32 v80, 0
	v_mov_b32_e32 v81, 0
	v_mov_b32_e32 v82, 0
	v_mov_b32_e32 v83, 0
	v_add_u32_e32 v112, 14, v70
	v_cmp_gt_u32_e32 vcc, s19, v112
	s_and_saveexec_b64 s[4:5], vcc
	s_cbranch_execz .Lcv1_0
	v_lshl_add_u64 v[80:81], v[60:61], 0, v[128:129]
	v_add_co_u32_e32 v80, vcc, 0x3196000, v80
	s_nop 1
	v_addc_co_u32_e32 v81, vcc, 0, v81, vcc
	global_load_dwordx4 v[80:83], v[80:81], off offset:576
.Lcv1_0:
	s_or_b64 exec, exec, s[4:5]
	v_mov_b32_e32 v84, 0
	v_mov_b32_e32 v85, 0
	v_mov_b32_e32 v86, 0
	v_mov_b32_e32 v87, 0
	v_add_u32_e32 v112, 15, v70
	v_cmp_gt_u32_e32 vcc, s19, v112
	s_and_saveexec_b64 s[4:5], vcc
	s_cbranch_execz .Lcv1_1
	v_lshl_add_u64 v[84:85], v[64:65], 0, v[128:129]
	v_add_co_u32_e32 v84, vcc, 0x3196000, v84
	s_nop 1
	v_addc_co_u32_e32 v85, vcc, 0, v85, vcc
	global_load_dwordx4 v[84:87], v[84:85], off offset:576
.Lcv1_1:
	s_or_b64 exec, exec, s[4:5]
	v_mov_b32_e32 v88, 0
	v_mov_b32_e32 v89, 0
	v_mov_b32_e32 v90, 0
	v_mov_b32_e32 v91, 0
	v_add_u32_e32 v112, 16, v70
	v_cmp_gt_u32_e32 vcc, s19, v112
	s_and_saveexec_b64 s[4:5], vcc
	s_cbranch_execz .Lcv1_2
	v_lshl_add_u64 v[88:89], v[58:59], 0, v[128:129]
	v_add_co_u32_e32 v88, vcc, 0x3196000, v88
	s_nop 1
	v_addc_co_u32_e32 v89, vcc, 0, v89, vcc
	global_load_dwordx4 v[88:91], v[88:89], off offset:576
.Lcv1_2:
	s_or_b64 exec, exec, s[4:5]
	v_mov_b32_e32 v92, 0
	v_mov_b32_e32 v93, 0
	v_mov_b32_e32 v94, 0
	v_mov_b32_e32 v95, 0
	v_add_u32_e32 v112, 17, v70
	v_cmp_gt_u32_e32 vcc, s19, v112
	s_and_saveexec_b64 s[4:5], vcc
	s_cbranch_execz .Lcv1_3
	v_lshl_add_u64 v[92:93], v[62:63], 0, v[128:129]
	v_add_co_u32_e32 v92, vcc, 0x3196000, v92
	s_nop 1
	v_addc_co_u32_e32 v93, vcc, 0, v93, vcc
	global_load_dwordx4 v[92:95], v[92:93], off offset:576
.Lcv1_3:
	s_or_b64 exec, exec, s[4:5]
	v_mov_b32_e32 v96, 0
	v_mov_b32_e32 v97, 0
	v_mov_b32_e32 v98, 0
	v_mov_b32_e32 v99, 0
	v_add_u32_e32 v112, 22, v70
	v_cmp_gt_u32_e32 vcc, s19, v112
	s_and_saveexec_b64 s[4:5], vcc
	s_cbranch_execz .Lcv1_4
	v_lshl_add_u64 v[96:97], v[56:57], 0, v[128:129]
	v_add_co_u32_e32 v96, vcc, 0x3196000, v96
	s_nop 1
	v_addc_co_u32_e32 v97, vcc, 0, v97, vcc
	global_load_dwordx4 v[96:99], v[96:97], off offset:576
.Lcv1_4:
	s_or_b64 exec, exec, s[4:5]
	v_mov_b32_e32 v100, 0
	v_mov_b32_e32 v101, 0
	v_mov_b32_e32 v102, 0
	v_mov_b32_e32 v103, 0
	v_add_u32_e32 v112, 23, v70
	v_cmp_gt_u32_e32 vcc, s19, v112
	s_and_saveexec_b64 s[4:5], vcc
	s_cbranch_execz .Lcv1_5
	v_lshl_add_u64 v[100:101], v[54:55], 0, v[128:129]
	v_add_co_u32_e32 v100, vcc, 0x3196000, v100
	s_nop 1
	v_addc_co_u32_e32 v101, vcc, 0, v101, vcc
	global_load_dwordx4 v[100:103], v[100:101], off offset:576
.Lcv1_5:
	s_or_b64 exec, exec, s[4:5]
	v_mov_b32_e32 v104, 0
	v_mov_b32_e32 v105, 0
	v_mov_b32_e32 v106, 0
	v_mov_b32_e32 v107, 0
	v_add_u32_e32 v112, 24, v70
	v_cmp_gt_u32_e32 vcc, s19, v112
	s_and_saveexec_b64 s[4:5], vcc
	s_cbranch_execz .Lcv1_6
	v_lshl_add_u64 v[104:105], v[50:51], 0, v[128:129]
	v_add_co_u32_e32 v104, vcc, 0x3196000, v104
	s_nop 1
	v_addc_co_u32_e32 v105, vcc, 0, v105, vcc
	global_load_dwordx4 v[104:107], v[104:105], off offset:576
.Lcv1_6:
	s_or_b64 exec, exec, s[4:5]
	v_mov_b32_e32 v108, 0
	v_mov_b32_e32 v109, 0
	v_mov_b32_e32 v110, 0
	v_mov_b32_e32 v111, 0
	v_add_u32_e32 v112, 25, v70
	v_cmp_gt_u32_e32 vcc, s19, v112
	s_and_saveexec_b64 s[4:5], vcc
	s_cbranch_execz .Lcv1_7
	v_lshl_add_u64 v[108:109], v[52:53], 0, v[128:129]
	v_add_co_u32_e32 v108, vcc, 0x3196000, v108
	s_nop 1
	v_addc_co_u32_e32 v109, vcc, 0, v109, vcc
	global_load_dwordx4 v[108:111], v[108:109], off offset:576
.Lcv1_7:
	s_or_b64 exec, exec, s[4:5]
	s_waitcnt vmcnt(0)
	s_waitcnt vmcnt(8)
	v_mov_b64_e32 v[14:15], v[6:7]
	v_mov_b64_e32 v[12:13], v[4:5]
	v_mov_b64_e32 v[10:11], v[2:3]
	v_mov_b64_e32 v[8:9], v[0:1]
	v_mov_b32_e32 v8, v80
	v_mov_b32_e32 v9, v81
	v_mov_b32_e32 v10, v82
	v_mov_b32_e32 v11, v83
	v_lshlrev_b32_e32 v72, 16, v8
	v_and_b32_e32 v73, 0xffff0000, v8
	v_lshlrev_b32_e32 v8, 16, v9
	v_and_b32_e32 v9, 0xffff0000, v9
	v_lshlrev_b32_e32 v12, 16, v10
	v_and_b32_e32 v13, 0xffff0000, v10
	v_lshlrev_b32_e32 v10, 16, v11
	v_and_b32_e32 v11, 0xffff0000, v11
	v_pk_fma_f32 v[14:15], v[18:19], v[10:11], v[6:7]
	v_pk_fma_f32 v[12:13], v[16:17], v[12:13], v[4:5]
	v_pk_fma_f32 v[10:11], v[22:23], v[8:9], v[2:3]
	v_pk_fma_f32 v[8:9], v[20:21], v[72:73], v[0:1]
	v_mov_b32_e32 v72, v84
	v_mov_b32_e32 v73, v85
	v_mov_b32_e32 v74, v86
	v_mov_b32_e32 v75, v87
	v_lshlrev_b32_e32 v76, 16, v72
	v_and_b32_e32 v77, 0xffff0000, v72
	v_lshlrev_b32_e32 v72, 16, v73
	v_and_b32_e32 v73, 0xffff0000, v73
	v_lshlrev_b32_e32 v78, 16, v74
	v_and_b32_e32 v79, 0xffff0000, v74
	v_lshlrev_b32_e32 v74, 16, v75
	v_and_b32_e32 v75, 0xffff0000, v75
	v_pk_fma_f32 v[14:15], v[26:27], v[74:75], v[14:15]
	v_pk_fma_f32 v[12:13], v[24:25], v[78:79], v[12:13]
	v_pk_fma_f32 v[10:11], v[30:31], v[72:73], v[10:11]
	v_pk_fma_f32 v[8:9], v[28:29], v[76:77], v[8:9]
	v_mov_b32_e32 v72, v88
	v_mov_b32_e32 v73, v89
	v_mov_b32_e32 v74, v90
	v_mov_b32_e32 v75, v91
	v_lshlrev_b32_e32 v76, 16, v72
	v_and_b32_e32 v77, 0xffff0000, v72
	v_lshlrev_b32_e32 v72, 16, v73
	v_and_b32_e32 v73, 0xffff0000, v73
	v_lshlrev_b32_e32 v78, 16, v74
	v_and_b32_e32 v79, 0xffff0000, v74
	v_lshlrev_b32_e32 v74, 16, v75
	v_and_b32_e32 v75, 0xffff0000, v75
	v_pk_fma_f32 v[14:15], v[38:39], v[74:75], v[14:15]
	v_pk_fma_f32 v[12:13], v[36:37], v[78:79], v[12:13]
	v_pk_fma_f32 v[10:11], v[34:35], v[72:73], v[10:11]
	v_pk_fma_f32 v[8:9], v[32:33], v[76:77], v[8:9]
	v_mov_b32_e32 v72, v92
	v_mov_b32_e32 v73, v93
	v_mov_b32_e32 v74, v94
	v_mov_b32_e32 v75, v95
	v_lshlrev_b32_e32 v76, 16, v72
	v_and_b32_e32 v77, 0xffff0000, v72
	v_lshlrev_b32_e32 v72, 16, v73
	v_and_b32_e32 v73, 0xffff0000, v73
	v_lshlrev_b32_e32 v78, 16, v74
	v_and_b32_e32 v79, 0xffff0000, v74
	v_lshlrev_b32_e32 v74, 16, v75
	v_and_b32_e32 v75, 0xffff0000, v75
	v_pk_fma_f32 v[14:15], v[46:47], v[74:75], v[14:15]
	v_pk_fma_f32 v[12:13], v[44:45], v[78:79], v[12:13]
	v_pk_fma_f32 v[10:11], v[42:43], v[72:73], v[10:11]
	v_pk_fma_f32 v[8:9], v[40:41], v[76:77], v[8:9]
	v_mul_f32_e32 v71, 0xbfb8aa3b, v8
	v_exp_f32_e32 v71, v71
	s_nop 0
	v_add_f32_e32 v71, 1.0, v71
	v_rcp_f32_e32 v72, v71
	v_mul_f32_e32 v71, 0xbfb8aa3b, v9
	v_exp_f32_e32 v71, v71
	s_nop 0
	v_add_f32_e32 v71, 1.0, v71
	v_rcp_f32_e32 v73, v71
	s_nop 0
	v_pk_mul_f32 v[8:9], v[8:9], v[72:73]
	s_nop 0
	v_cvt_pk_bf16_f32 v8, v8, v9
	v_mul_f32_e32 v9, 0xbfb8aa3b, v10
	v_exp_f32_e32 v9, v9
	s_nop 0
	v_add_f32_e32 v9, 1.0, v9
	v_rcp_f32_e32 v72, v9
	v_mul_f32_e32 v9, 0xbfb8aa3b, v11
	v_exp_f32_e32 v9, v9
	s_nop 0
	v_add_f32_e32 v9, 1.0, v9
	v_rcp_f32_e32 v73, v9
	s_nop 0
	v_pk_mul_f32 v[10:11], v[10:11], v[72:73]
	s_nop 0
	v_cvt_pk_bf16_f32 v9, v10, v11
	v_mul_f32_e32 v10, 0xbfb8aa3b, v12
	v_mul_f32_e32 v11, 0xbfb8aa3b, v13
	v_exp_f32_e32 v10, v10
	v_exp_f32_e32 v11, v11
	v_add_f32_e32 v10, 1.0, v10
	v_add_f32_e32 v11, 1.0, v11
	v_rcp_f32_e32 v10, v10
	v_rcp_f32_e32 v11, v11
	s_nop 0
	v_pk_mul_f32 v[10:11], v[12:13], v[10:11]
	s_nop 0
	v_cvt_pk_bf16_f32 v10, v10, v11
	v_mul_f32_e32 v11, 0xbfb8aa3b, v14
	v_exp_f32_e32 v11, v11
	s_nop 0
	v_add_f32_e32 v11, 1.0, v11
	v_rcp_f32_e32 v12, v11
	v_mul_f32_e32 v11, 0xbfb8aa3b, v15
	v_exp_f32_e32 v11, v11
	s_nop 0
	v_add_f32_e32 v11, 1.0, v11
	v_rcp_f32_e32 v13, v11
	s_nop 0
	v_pk_mul_f32 v[12:13], v[14:15], v[12:13]
	s_nop 0
	v_cvt_pk_bf16_f32 v11, v12, v13
	ds_write_b128 v69, v[8:11]
	v_mov_b64_e32 v[14:15], v[6:7]
	v_mov_b64_e32 v[12:13], v[4:5]
	v_mov_b64_e32 v[10:11], v[2:3]
	v_mov_b64_e32 v[8:9], v[0:1]
	v_mov_b32_e32 v8, v96
	v_mov_b32_e32 v9, v97
	v_mov_b32_e32 v10, v98
	v_mov_b32_e32 v11, v99
	v_lshlrev_b32_e32 v72, 16, v8
	v_and_b32_e32 v73, 0xffff0000, v8
	v_lshlrev_b32_e32 v8, 16, v9
	v_and_b32_e32 v9, 0xffff0000, v9
	v_lshlrev_b32_e32 v12, 16, v10
	v_and_b32_e32 v13, 0xffff0000, v10
	v_lshlrev_b32_e32 v10, 16, v11
	v_and_b32_e32 v11, 0xffff0000, v11
	v_pk_fma_f32 v[14:15], v[18:19], v[10:11], v[6:7]
	v_pk_fma_f32 v[12:13], v[16:17], v[12:13], v[4:5]
	v_pk_fma_f32 v[10:11], v[22:23], v[8:9], v[2:3]
	v_pk_fma_f32 v[8:9], v[20:21], v[72:73], v[0:1]
	v_mov_b32_e32 v72, v100
	v_mov_b32_e32 v73, v101
	v_mov_b32_e32 v74, v102
	v_mov_b32_e32 v75, v103
	v_lshlrev_b32_e32 v76, 16, v72
	v_and_b32_e32 v77, 0xffff0000, v72
	v_lshlrev_b32_e32 v72, 16, v73
	v_and_b32_e32 v73, 0xffff0000, v73
	v_lshlrev_b32_e32 v78, 16, v74
	v_and_b32_e32 v79, 0xffff0000, v74
	v_lshlrev_b32_e32 v74, 16, v75
	v_and_b32_e32 v75, 0xffff0000, v75
	v_pk_fma_f32 v[14:15], v[26:27], v[74:75], v[14:15]
	v_pk_fma_f32 v[12:13], v[24:25], v[78:79], v[12:13]
	v_pk_fma_f32 v[10:11], v[30:31], v[72:73], v[10:11]
	v_pk_fma_f32 v[8:9], v[28:29], v[76:77], v[8:9]
	v_mov_b32_e32 v72, v104
	v_mov_b32_e32 v73, v105
	v_mov_b32_e32 v74, v106
	v_mov_b32_e32 v75, v107
	v_lshlrev_b32_e32 v76, 16, v72
	v_and_b32_e32 v77, 0xffff0000, v72
	v_lshlrev_b32_e32 v72, 16, v73
	v_and_b32_e32 v73, 0xffff0000, v73
	v_lshlrev_b32_e32 v78, 16, v74
	v_and_b32_e32 v79, 0xffff0000, v74
	v_lshlrev_b32_e32 v74, 16, v75
	v_and_b32_e32 v75, 0xffff0000, v75
	v_pk_fma_f32 v[14:15], v[38:39], v[74:75], v[14:15]
	v_pk_fma_f32 v[12:13], v[36:37], v[78:79], v[12:13]
	v_pk_fma_f32 v[10:11], v[34:35], v[72:73], v[10:11]
	v_pk_fma_f32 v[8:9], v[32:33], v[76:77], v[8:9]
	v_mov_b32_e32 v70, v108
	v_mov_b32_e32 v71, v109
	v_mov_b32_e32 v72, v110
	v_mov_b32_e32 v73, v111
	v_lshlrev_b32_e32 v74, 16, v70
	v_and_b32_e32 v75, 0xffff0000, v70
	v_lshlrev_b32_e32 v70, 16, v71
	v_and_b32_e32 v71, 0xffff0000, v71
	v_lshlrev_b32_e32 v76, 16, v72
	v_and_b32_e32 v77, 0xffff0000, v72
	v_lshlrev_b32_e32 v72, 16, v73
	v_and_b32_e32 v73, 0xffff0000, v73
	v_pk_fma_f32 v[14:15], v[46:47], v[72:73], v[14:15]
	v_pk_fma_f32 v[12:13], v[44:45], v[76:77], v[12:13]
	v_pk_fma_f32 v[10:11], v[42:43], v[70:71], v[10:11]
	v_pk_fma_f32 v[8:9], v[40:41], v[74:75], v[8:9]
	s_branch .LBB0_496

.Lat_loop:
	global_load_dwordx4 v[146:149], v[160:161], off
	global_load_dwordx4 v[150:153], v[162:163], off
	v_lshl_add_u64 v[160:161], v[160:161], 0, s[54:55]
	v_lshl_add_u64 v[162:163], v[162:163], 0, s[88:89]
	s_waitcnt lgkmcnt(3)
	v_mfma_f32_32x32x16_bf16 v[112:127], v[164:167], v[138:141], v[80:95]
	v_exp_f32_e32 v96, v96
	v_exp_f32_e32 v97, v97
	s_waitcnt lgkmcnt(2)
	v_mfma_f32_32x32x16_bf16 v[112:127], v[168:171], v[142:145], v[112:127]
	ds_read_b128 v[164:167], v175 offset:2560
	ds_read_b128 v[168:171], v175 offset:2592
	v_exp_f32_e32 v98, v98
	v_exp_f32_e32 v99, v99
	v_exp_f32_e32 v100, v100
	v_mfma_f32_32x32x16_bf16 v[32:47], v[226:229], v[184:187], v[32:47]
	ds_read_b128 v[226:229], v174 offset:10240
	v_exp_f32_e32 v101, v101
	v_exp_f32_e32 v102, v102
	v_exp_f32_e32 v103, v103
	v_mfma_f32_32x32x16_bf16 v[0:15], v[234:237], v[184:187], v[0:15]
	ds_read_b128 v[234:237], v174 offset:14848
	v_exp_f32_e32 v104, v104
	v_exp_f32_e32 v105, v105
	v_exp_f32_e32 v106, v106
	v_mfma_f32_32x32x16_bf16 v[32:47], v[230:233], v[188:191], v[32:47]
	ds_read_b128 v[230:233], v174 offset:10272
	v_exp_f32_e32 v107, v107
	v_exp_f32_e32 v108, v108
	v_exp_f32_e32 v109, v109
	v_mfma_f32_32x32x16_bf16 v[0:15], v[238:241], v[188:191], v[0:15]
	ds_read_b128 v[238:241], v174 offset:14880
	v_exp_f32_e32 v110, v110
	v_exp_f32_e32 v111, v111
	v_pk_add_f32 v[200:201], v[96:97], v[200:201]
	v_cvt_pk_bf16_f32 v176, v96, v97
	v_pk_add_f32 v[200:201], v[98:99], v[200:201]
	v_cvt_pk_bf16_f32 v177, v98, v99
	v_pk_add_f32 v[200:201], v[100:101], v[200:201]
	v_cvt_pk_bf16_f32 v178, v100, v101
	v_pk_add_f32 v[200:201], v[102:103], v[200:201]
	v_cvt_pk_bf16_f32 v179, v102, v103
	v_pk_add_f32 v[200:201], v[104:105], v[200:201]
	v_cvt_pk_bf16_f32 v180, v104, v105
	v_pk_add_f32 v[200:201], v[106:107], v[200:201]
	v_cvt_pk_bf16_f32 v181, v106, v107
	v_pk_add_f32 v[200:201], v[108:109], v[200:201]
	v_cvt_pk_bf16_f32 v182, v108, v109
	v_pk_add_f32 v[200:201], v[110:111], v[200:201]
	v_cvt_pk_bf16_f32 v183, v110, v111
	s_waitcnt lgkmcnt(5)
	v_mfma_f32_32x32x16_bf16 v[96:111], v[164:167], v[130:133], v[64:79]
	v_exp_f32_e32 v112, v112
	v_exp_f32_e32 v113, v113
	s_waitcnt lgkmcnt(4)
	v_mfma_f32_32x32x16_bf16 v[96:111], v[168:171], v[134:137], v[96:111]
	ds_read_b128 v[164:167], v175 offset:7680
	ds_read_b128 v[168:171], v175 offset:7712
	v_exp_f32_e32 v114, v114
	v_exp_f32_e32 v115, v115
	v_exp_f32_e32 v116, v116
	s_waitcnt lgkmcnt(5)
	v_mfma_f32_32x32x16_bf16 v[48:63], v[226:229], v[176:179], v[48:63]
	v_exp_f32_e32 v117, v117
	v_exp_f32_e32 v118, v118
	v_exp_f32_e32 v119, v119
	s_waitcnt lgkmcnt(4)
	v_mfma_f32_32x32x16_bf16 v[16:31], v[234:237], v[176:179], v[16:31]
	v_exp_f32_e32 v120, v120
	v_exp_f32_e32 v121, v121
	v_exp_f32_e32 v122, v122
	s_waitcnt lgkmcnt(3)
	v_mfma_f32_32x32x16_bf16 v[48:63], v[230:233], v[180:183], v[48:63]
	v_exp_f32_e32 v123, v123
	v_exp_f32_e32 v124, v124
	v_exp_f32_e32 v125, v125
	s_waitcnt lgkmcnt(2)
	v_mfma_f32_32x32x16_bf16 v[16:31], v[238:241], v[180:183], v[16:31]
	v_exp_f32_e32 v126, v126
	v_exp_f32_e32 v127, v127
	v_pk_add_f32 v[202:203], v[112:113], v[202:203]
	v_cvt_pk_bf16_f32 v184, v112, v113
	v_pk_add_f32 v[202:203], v[114:115], v[202:203]
	v_cvt_pk_bf16_f32 v185, v114, v115
	v_pk_add_f32 v[202:203], v[116:117], v[202:203]
	v_cvt_pk_bf16_f32 v186, v116, v117
	v_pk_add_f32 v[202:203], v[118:119], v[202:203]
	v_cvt_pk_bf16_f32 v187, v118, v119
	v_pk_add_f32 v[202:203], v[120:121], v[202:203]
	v_cvt_pk_bf16_f32 v188, v120, v121
	v_pk_add_f32 v[202:203], v[122:123], v[202:203]
	v_cvt_pk_bf16_f32 v189, v122, v123
	v_pk_add_f32 v[202:203], v[124:125], v[202:203]
	v_cvt_pk_bf16_f32 v190, v124, v125
	v_pk_add_f32 v[202:203], v[126:127], v[202:203]
	v_cvt_pk_bf16_f32 v191, v126, v127
	s_waitcnt lgkmcnt(1)
	v_mfma_f32_32x32x16_bf16 v[112:127], v[164:167], v[138:141], v[80:95]
	v_exp_f32_e32 v96, v96
	v_exp_f32_e32 v97, v97
	s_waitcnt lgkmcnt(0)
	v_mfma_f32_32x32x16_bf16 v[112:127], v[168:171], v[142:145], v[112:127]
	s_barrier
	ds_read_b128 v[164:167], v175 offset:19456
	ds_read_b128 v[168:171], v175 offset:19488
	v_exp_f32_e32 v98, v98
	v_exp_f32_e32 v99, v99
	v_exp_f32_e32 v100, v100
	v_mfma_f32_32x32x16_bf16 v[32:47], v[226:229], v[184:187], v[32:47]
	ds_read_b128 v[226:229], v174 offset:10304
	v_exp_f32_e32 v101, v101
	v_exp_f32_e32 v102, v102
	v_exp_f32_e32 v103, v103
	v_mfma_f32_32x32x16_bf16 v[0:15], v[234:237], v[184:187], v[0:15]
	ds_read_b128 v[234:237], v174 offset:14912
	v_exp_f32_e32 v104, v104
	v_exp_f32_e32 v105, v105
	v_exp_f32_e32 v106, v106
	v_mfma_f32_32x32x16_bf16 v[32:47], v[230:233], v[188:191], v[32:47]
	ds_read_b128 v[230:233], v174 offset:10336
	v_exp_f32_e32 v107, v107
	v_exp_f32_e32 v108, v108
	v_exp_f32_e32 v109, v109
	v_mfma_f32_32x32x16_bf16 v[0:15], v[238:241], v[188:191], v[0:15]
	ds_read_b128 v[238:241], v174 offset:14944
	v_exp_f32_e32 v110, v110
	v_exp_f32_e32 v111, v111
	v_pk_add_f32 v[200:201], v[96:97], v[200:201]
	v_cvt_pk_bf16_f32 v176, v96, v97
	v_pk_add_f32 v[200:201], v[98:99], v[200:201]
	v_cvt_pk_bf16_f32 v177, v98, v99
	v_pk_add_f32 v[200:201], v[100:101], v[200:201]
	v_cvt_pk_bf16_f32 v178, v100, v101
	v_pk_add_f32 v[200:201], v[102:103], v[200:201]
	v_cvt_pk_bf16_f32 v179, v102, v103
	v_pk_add_f32 v[200:201], v[104:105], v[200:201]
	v_cvt_pk_bf16_f32 v180, v104, v105
	v_pk_add_f32 v[200:201], v[106:107], v[200:201]
	v_cvt_pk_bf16_f32 v181, v106, v107
	v_pk_add_f32 v[200:201], v[108:109], v[200:201]
	v_cvt_pk_bf16_f32 v182, v108, v109
	v_pk_add_f32 v[200:201], v[110:111], v[200:201]
	v_cvt_pk_bf16_f32 v183, v110, v111
	s_waitcnt lgkmcnt(5)
	v_mfma_f32_32x32x16_bf16 v[96:111], v[164:167], v[130:133], v[64:79]
	v_exp_f32_e32 v112, v112
	v_exp_f32_e32 v113, v113
	s_waitcnt lgkmcnt(4)
	v_mfma_f32_32x32x16_bf16 v[96:111], v[168:171], v[134:137], v[96:111]
	ds_read_b128 v[164:167], v175 offset:24576
	ds_read_b128 v[168:171], v175 offset:24608
	v_exp_f32_e32 v114, v114
	v_exp_f32_e32 v115, v115
	v_exp_f32_e32 v116, v116
	s_waitcnt lgkmcnt(5)
	v_mfma_f32_32x32x16_bf16 v[48:63], v[226:229], v[176:179], v[48:63]
	v_exp_f32_e32 v117, v117
	v_exp_f32_e32 v118, v118
	v_exp_f32_e32 v119, v119
	s_waitcnt lgkmcnt(4)
	v_mfma_f32_32x32x16_bf16 v[16:31], v[234:237], v[176:179], v[16:31]
	v_exp_f32_e32 v120, v120
	v_exp_f32_e32 v121, v121
	v_exp_f32_e32 v122, v122
	s_waitcnt lgkmcnt(3)
	v_mfma_f32_32x32x16_bf16 v[48:63], v[230:233], v[180:183], v[48:63]
	v_exp_f32_e32 v123, v123
	v_exp_f32_e32 v124, v124
	v_exp_f32_e32 v125, v125
	s_waitcnt lgkmcnt(2)
	v_mfma_f32_32x32x16_bf16 v[16:31], v[238:241], v[180:183], v[16:31]
	s_waitcnt vmcnt(1)
	ds_write_b128 v155, v[146:149] offset:38912
	s_waitcnt vmcnt(0)
	ds_write_b128 v157, v[150:153] offset:49152
	v_exp_f32_e32 v126, v126
	v_exp_f32_e32 v127, v127
	v_pk_add_f32 v[202:203], v[112:113], v[202:203]
	v_cvt_pk_bf16_f32 v184, v112, v113
	v_pk_add_f32 v[202:203], v[114:115], v[202:203]
	v_cvt_pk_bf16_f32 v185, v114, v115
	v_pk_add_f32 v[202:203], v[116:117], v[202:203]
	v_cvt_pk_bf16_f32 v186, v116, v117
	v_pk_add_f32 v[202:203], v[118:119], v[202:203]
	v_cvt_pk_bf16_f32 v187, v118, v119
	v_pk_add_f32 v[202:203], v[120:121], v[202:203]
	v_cvt_pk_bf16_f32 v188, v120, v121
	v_pk_add_f32 v[202:203], v[122:123], v[202:203]
	v_cvt_pk_bf16_f32 v189, v122, v123
	v_pk_add_f32 v[202:203], v[124:125], v[202:203]
	v_cvt_pk_bf16_f32 v190, v124, v125
	v_pk_add_f32 v[202:203], v[126:127], v[202:203]
	v_cvt_pk_bf16_f32 v191, v126, v127
	s_cmp_eq_u32 s2, 43
	s_cbranch_scc1 .Lat_skip1
	global_load_dwordx4 v[146:149], v[160:161], off
	global_load_dwordx4 v[150:153], v[162:163], off
	v_lshl_add_u64 v[160:161], v[160:161], 0, s[54:55]
	v_lshl_add_u64 v[162:163], v[162:163], 0, s[88:89]
.Lat_skip1:
	s_waitcnt lgkmcnt(3)
	v_mfma_f32_32x32x16_bf16 v[112:127], v[164:167], v[138:141], v[80:95]
	v_exp_f32_e32 v96, v96
	v_exp_f32_e32 v97, v97
	s_waitcnt lgkmcnt(2)
	v_mfma_f32_32x32x16_bf16 v[112:127], v[168:171], v[142:145], v[112:127]
	ds_read_b128 v[164:167], v175 offset:22016
	ds_read_b128 v[168:171], v175 offset:22048
	v_exp_f32_e32 v98, v98
	v_exp_f32_e32 v99, v99
	v_exp_f32_e32 v100, v100
	v_mfma_f32_32x32x16_bf16 v[32:47], v[226:229], v[184:187], v[32:47]
	ds_read_b128 v[226:229], v174 offset:29696
	v_exp_f32_e32 v101, v101
	v_exp_f32_e32 v102, v102
	v_exp_f32_e32 v103, v103
	v_mfma_f32_32x32x16_bf16 v[0:15], v[234:237], v[184:187], v[0:15]
	ds_read_b128 v[234:237], v174 offset:34304
	v_exp_f32_e32 v104, v104
	v_exp_f32_e32 v105, v105
	v_exp_f32_e32 v106, v106
	v_mfma_f32_32x32x16_bf16 v[32:47], v[230:233], v[188:191], v[32:47]
	ds_read_b128 v[230:233], v174 offset:29728
	v_exp_f32_e32 v107, v107
	v_exp_f32_e32 v108, v108
	v_exp_f32_e32 v109, v109
	v_mfma_f32_32x32x16_bf16 v[0:15], v[238:241], v[188:191], v[0:15]
	ds_read_b128 v[238:241], v174 offset:34336
	v_exp_f32_e32 v110, v110
	v_exp_f32_e32 v111, v111
	v_pk_add_f32 v[200:201], v[96:97], v[200:201]
	v_cvt_pk_bf16_f32 v176, v96, v97
	v_pk_add_f32 v[200:201], v[98:99], v[200:201]
	v_cvt_pk_bf16_f32 v177, v98, v99
	v_pk_add_f32 v[200:201], v[100:101], v[200:201]
	v_cvt_pk_bf16_f32 v178, v100, v101
	v_pk_add_f32 v[200:201], v[102:103], v[200:201]
	v_cvt_pk_bf16_f32 v179, v102, v103
	v_pk_add_f32 v[200:201], v[104:105], v[200:201]
	v_cvt_pk_bf16_f32 v180, v104, v105
	v_pk_add_f32 v[200:201], v[106:107], v[200:201]
	v_cvt_pk_bf16_f32 v181, v106, v107
	v_pk_add_f32 v[200:201], v[108:109], v[200:201]
	v_cvt_pk_bf16_f32 v182, v108, v109
	v_pk_add_f32 v[200:201], v[110:111], v[200:201]
	v_cvt_pk_bf16_f32 v183, v110, v111
	s_waitcnt lgkmcnt(5)
	v_mfma_f32_32x32x16_bf16 v[96:111], v[164:167], v[130:133], v[64:79]
	v_exp_f32_e32 v112, v112
	v_exp_f32_e32 v113, v113
	s_waitcnt lgkmcnt(4)
	v_mfma_f32_32x32x16_bf16 v[96:111], v[168:171], v[134:137], v[96:111]
	ds_read_b128 v[164:167], v175 offset:27136
	ds_read_b128 v[168:171], v175 offset:27168
	v_exp_f32_e32 v114, v114
	v_exp_f32_e32 v115, v115
	v_exp_f32_e32 v116, v116
	s_waitcnt lgkmcnt(5)
	v_mfma_f32_32x32x16_bf16 v[48:63], v[226:229], v[176:179], v[48:63]
	v_exp_f32_e32 v117, v117
	v_exp_f32_e32 v118, v118
	v_exp_f32_e32 v119, v119
	s_waitcnt lgkmcnt(4)
	v_mfma_f32_32x32x16_bf16 v[16:31], v[234:237], v[176:179], v[16:31]
	v_exp_f32_e32 v120, v120
	v_exp_f32_e32 v121, v121
	v_exp_f32_e32 v122, v122
	s_waitcnt lgkmcnt(3)
	v_mfma_f32_32x32x16_bf16 v[48:63], v[230:233], v[180:183], v[48:63]
	v_exp_f32_e32 v123, v123
	v_exp_f32_e32 v124, v124
	v_exp_f32_e32 v125, v125
	s_waitcnt lgkmcnt(2)
	v_mfma_f32_32x32x16_bf16 v[16:31], v[238:241], v[180:183], v[16:31]
	v_exp_f32_e32 v126, v126
	v_exp_f32_e32 v127, v127
	v_pk_add_f32 v[202:203], v[112:113], v[202:203]
	v_cvt_pk_bf16_f32 v184, v112, v113
	v_pk_add_f32 v[202:203], v[114:115], v[202:203]
	v_cvt_pk_bf16_f32 v185, v114, v115
	v_pk_add_f32 v[202:203], v[116:117], v[202:203]
	v_cvt_pk_bf16_f32 v186, v116, v117
	v_pk_add_f32 v[202:203], v[118:119], v[202:203]
	v_cvt_pk_bf16_f32 v187, v118, v119
	v_pk_add_f32 v[202:203], v[120:121], v[202:203]
	v_cvt_pk_bf16_f32 v188, v120, v121
	v_pk_add_f32 v[202:203], v[122:123], v[202:203]
	v_cvt_pk_bf16_f32 v189, v122, v123
	v_pk_add_f32 v[202:203], v[124:125], v[202:203]
	v_cvt_pk_bf16_f32 v190, v124, v125
	v_pk_add_f32 v[202:203], v[126:127], v[202:203]
	v_cvt_pk_bf16_f32 v191, v126, v127
	s_waitcnt lgkmcnt(1)
	v_mfma_f32_32x32x16_bf16 v[112:127], v[164:167], v[138:141], v[80:95]
	v_exp_f32_e32 v96, v96
	v_exp_f32_e32 v97, v97
	s_waitcnt lgkmcnt(0)
	v_mfma_f32_32x32x16_bf16 v[112:127], v[168:171], v[142:145], v[112:127]
	s_barrier
	ds_read_b128 v[164:167], v175 offset:38912
	ds_read_b128 v[168:171], v175 offset:38944
	v_exp_f32_e32 v98, v98
	v_exp_f32_e32 v99, v99
	v_exp_f32_e32 v100, v100
	v_mfma_f32_32x32x16_bf16 v[32:47], v[226:229], v[184:187], v[32:47]
	ds_read_b128 v[226:229], v174 offset:29760
	v_exp_f32_e32 v101, v101
	v_exp_f32_e32 v102, v102
	v_exp_f32_e32 v103, v103
	v_mfma_f32_32x32x16_bf16 v[0:15], v[234:237], v[184:187], v[0:15]
	ds_read_b128 v[234:237], v174 offset:34368
	v_exp_f32_e32 v104, v104
	v_exp_f32_e32 v105, v105
	v_exp_f32_e32 v106, v106
	v_mfma_f32_32x32x16_bf16 v[32:47], v[230:233], v[188:191], v[32:47]
	ds_read_b128 v[230:233], v174 offset:29792
	v_exp_f32_e32 v107, v107
	v_exp_f32_e32 v108, v108
	v_exp_f32_e32 v109, v109
	v_mfma_f32_32x32x16_bf16 v[0:15], v[238:241], v[188:191], v[0:15]
	ds_read_b128 v[238:241], v174 offset:34400
	v_exp_f32_e32 v110, v110
	v_exp_f32_e32 v111, v111
	v_pk_add_f32 v[200:201], v[96:97], v[200:201]
	v_cvt_pk_bf16_f32 v176, v96, v97
	v_pk_add_f32 v[200:201], v[98:99], v[200:201]
	v_cvt_pk_bf16_f32 v177, v98, v99
	v_pk_add_f32 v[200:201], v[100:101], v[200:201]
	v_cvt_pk_bf16_f32 v178, v100, v101
	v_pk_add_f32 v[200:201], v[102:103], v[200:201]
	v_cvt_pk_bf16_f32 v179, v102, v103
	v_pk_add_f32 v[200:201], v[104:105], v[200:201]
	v_cvt_pk_bf16_f32 v180, v104, v105
	v_pk_add_f32 v[200:201], v[106:107], v[200:201]
	v_cvt_pk_bf16_f32 v181, v106, v107
	v_pk_add_f32 v[200:201], v[108:109], v[200:201]
	v_cvt_pk_bf16_f32 v182, v108, v109
	v_pk_add_f32 v[200:201], v[110:111], v[200:201]
	v_cvt_pk_bf16_f32 v183, v110, v111
	s_waitcnt lgkmcnt(5)
	v_mfma_f32_32x32x16_bf16 v[96:111], v[164:167], v[130:133], v[64:79]
	v_exp_f32_e32 v112, v112
	v_exp_f32_e32 v113, v113
	s_waitcnt lgkmcnt(4)
	v_mfma_f32_32x32x16_bf16 v[96:111], v[168:171], v[134:137], v[96:111]
	ds_read_b128 v[164:167], v175 offset:44032
	ds_read_b128 v[168:171], v175 offset:44064
	v_exp_f32_e32 v114, v114
	v_exp_f32_e32 v115, v115
	v_exp_f32_e32 v116, v116
	s_waitcnt lgkmcnt(5)
	v_mfma_f32_32x32x16_bf16 v[48:63], v[226:229], v[176:179], v[48:63]
	v_exp_f32_e32 v117, v117
	v_exp_f32_e32 v118, v118
	v_exp_f32_e32 v119, v119
	s_waitcnt lgkmcnt(4)
	v_mfma_f32_32x32x16_bf16 v[16:31], v[234:237], v[176:179], v[16:31]
	v_exp_f32_e32 v120, v120
	v_exp_f32_e32 v121, v121
	v_exp_f32_e32 v122, v122
	s_waitcnt lgkmcnt(3)
	v_mfma_f32_32x32x16_bf16 v[48:63], v[230:233], v[180:183], v[48:63]
	v_exp_f32_e32 v123, v123
	v_exp_f32_e32 v124, v124
	v_exp_f32_e32 v125, v125
	s_waitcnt lgkmcnt(2)
	v_mfma_f32_32x32x16_bf16 v[16:31], v[238:241], v[180:183], v[16:31]
	s_waitcnt vmcnt(1)
	ds_write_b128 v155, v[146:149] offset:0
	s_waitcnt vmcnt(0)
	ds_write_b128 v157, v[150:153] offset:10240
	v_exp_f32_e32 v126, v126
	v_exp_f32_e32 v127, v127
	v_pk_add_f32 v[202:203], v[112:113], v[202:203]
	v_cvt_pk_bf16_f32 v184, v112, v113
	v_pk_add_f32 v[202:203], v[114:115], v[202:203]
	v_cvt_pk_bf16_f32 v185, v114, v115
	v_pk_add_f32 v[202:203], v[116:117], v[202:203]
	v_cvt_pk_bf16_f32 v186, v116, v117
	v_pk_add_f32 v[202:203], v[118:119], v[202:203]
	v_cvt_pk_bf16_f32 v187, v118, v119
	v_pk_add_f32 v[202:203], v[120:121], v[202:203]
	v_cvt_pk_bf16_f32 v188, v120, v121
	v_pk_add_f32 v[202:203], v[122:123], v[202:203]
	v_cvt_pk_bf16_f32 v189, v122, v123
	v_pk_add_f32 v[202:203], v[124:125], v[202:203]
	v_cvt_pk_bf16_f32 v190, v124, v125
	v_pk_add_f32 v[202:203], v[126:127], v[202:203]
	v_cvt_pk_bf16_f32 v191, v126, v127
	s_cmp_eq_u32 s2, 43
	s_cbranch_scc1 .Lat_skip2
	global_load_dwordx4 v[146:149], v[160:161], off
	global_load_dwordx4 v[150:153], v[162:163], off
	v_lshl_add_u64 v[160:161], v[160:161], 0, s[54:55]
	v_lshl_add_u64 v[162:163], v[162:163], 0, s[88:89]
.Lat_skip2:
	s_waitcnt lgkmcnt(3)
	v_mfma_f32_32x32x16_bf16 v[112:127], v[164:167], v[138:141], v[80:95]
	v_exp_f32_e32 v96, v96
	v_exp_f32_e32 v97, v97
	s_waitcnt lgkmcnt(2)
	v_mfma_f32_32x32x16_bf16 v[112:127], v[168:171], v[142:145], v[112:127]
	ds_read_b128 v[164:167], v175 offset:41472
	ds_read_b128 v[168:171], v175 offset:41504
	v_exp_f32_e32 v98, v98
	v_exp_f32_e32 v99, v99
	v_exp_f32_e32 v100, v100
	v_mfma_f32_32x32x16_bf16 v[32:47], v[226:229], v[184:187], v[32:47]
	ds_read_b128 v[226:229], v174 offset:49152
	v_exp_f32_e32 v101, v101
	v_exp_f32_e32 v102, v102
	v_exp_f32_e32 v103, v103
	v_mfma_f32_32x32x16_bf16 v[0:15], v[234:237], v[184:187], v[0:15]
	ds_read_b128 v[234:237], v174 offset:53760
	v_exp_f32_e32 v104, v104
	v_exp_f32_e32 v105, v105
	v_exp_f32_e32 v106, v106
	v_mfma_f32_32x32x16_bf16 v[32:47], v[230:233], v[188:191], v[32:47]
	ds_read_b128 v[230:233], v174 offset:49184
	v_exp_f32_e32 v107, v107
	v_exp_f32_e32 v108, v108
	v_exp_f32_e32 v109, v109
	v_mfma_f32_32x32x16_bf16 v[0:15], v[238:241], v[188:191], v[0:15]
	ds_read_b128 v[238:241], v174 offset:53792
	v_exp_f32_e32 v110, v110
	v_exp_f32_e32 v111, v111
	v_pk_add_f32 v[200:201], v[96:97], v[200:201]
	v_cvt_pk_bf16_f32 v176, v96, v97
	v_pk_add_f32 v[200:201], v[98:99], v[200:201]
	v_cvt_pk_bf16_f32 v177, v98, v99
	v_pk_add_f32 v[200:201], v[100:101], v[200:201]
	v_cvt_pk_bf16_f32 v178, v100, v101
	v_pk_add_f32 v[200:201], v[102:103], v[200:201]
	v_cvt_pk_bf16_f32 v179, v102, v103
	v_pk_add_f32 v[200:201], v[104:105], v[200:201]
	v_cvt_pk_bf16_f32 v180, v104, v105
	v_pk_add_f32 v[200:201], v[106:107], v[200:201]
	v_cvt_pk_bf16_f32 v181, v106, v107
	v_pk_add_f32 v[200:201], v[108:109], v[200:201]
	v_cvt_pk_bf16_f32 v182, v108, v109
	v_pk_add_f32 v[200:201], v[110:111], v[200:201]
	v_cvt_pk_bf16_f32 v183, v110, v111
	s_waitcnt lgkmcnt(5)
	v_mfma_f32_32x32x16_bf16 v[96:111], v[164:167], v[130:133], v[64:79]
	v_exp_f32_e32 v112, v112
	v_exp_f32_e32 v113, v113
	s_waitcnt lgkmcnt(4)
	v_mfma_f32_32x32x16_bf16 v[96:111], v[168:171], v[134:137], v[96:111]
	ds_read_b128 v[164:167], v175 offset:46592
	ds_read_b128 v[168:171], v175 offset:46624
	v_exp_f32_e32 v114, v114
	v_exp_f32_e32 v115, v115
	v_exp_f32_e32 v116, v116
	s_waitcnt lgkmcnt(5)
	v_mfma_f32_32x32x16_bf16 v[48:63], v[226:229], v[176:179], v[48:63]
	v_exp_f32_e32 v117, v117
	v_exp_f32_e32 v118, v118
	v_exp_f32_e32 v119, v119
	s_waitcnt lgkmcnt(4)
	v_mfma_f32_32x32x16_bf16 v[16:31], v[234:237], v[176:179], v[16:31]
	v_exp_f32_e32 v120, v120
	v_exp_f32_e32 v121, v121
	v_exp_f32_e32 v122, v122
	s_waitcnt lgkmcnt(3)
	v_mfma_f32_32x32x16_bf16 v[48:63], v[230:233], v[180:183], v[48:63]
	v_exp_f32_e32 v123, v123
	v_exp_f32_e32 v124, v124
	v_exp_f32_e32 v125, v125
	s_waitcnt lgkmcnt(2)
	v_mfma_f32_32x32x16_bf16 v[16:31], v[238:241], v[180:183], v[16:31]
	v_exp_f32_e32 v126, v126
	v_exp_f32_e32 v127, v127
	v_pk_add_f32 v[202:203], v[112:113], v[202:203]
	v_cvt_pk_bf16_f32 v184, v112, v113
	v_pk_add_f32 v[202:203], v[114:115], v[202:203]
	v_cvt_pk_bf16_f32 v185, v114, v115
	v_pk_add_f32 v[202:203], v[116:117], v[202:203]
	v_cvt_pk_bf16_f32 v186, v116, v117
	v_pk_add_f32 v[202:203], v[118:119], v[202:203]
	v_cvt_pk_bf16_f32 v187, v118, v119
	v_pk_add_f32 v[202:203], v[120:121], v[202:203]
	v_cvt_pk_bf16_f32 v188, v120, v121
	v_pk_add_f32 v[202:203], v[122:123], v[202:203]
	v_cvt_pk_bf16_f32 v189, v122, v123
	v_pk_add_f32 v[202:203], v[124:125], v[202:203]
	v_cvt_pk_bf16_f32 v190, v124, v125
	v_pk_add_f32 v[202:203], v[126:127], v[202:203]
	v_cvt_pk_bf16_f32 v191, v126, v127
	s_waitcnt lgkmcnt(1)
	v_mfma_f32_32x32x16_bf16 v[112:127], v[164:167], v[138:141], v[80:95]
	v_exp_f32_e32 v96, v96
	v_exp_f32_e32 v97, v97
	s_waitcnt lgkmcnt(0)
	v_mfma_f32_32x32x16_bf16 v[112:127], v[168:171], v[142:145], v[112:127]
	s_barrier
	ds_read_b128 v[164:167], v175 offset:0
	ds_read_b128 v[168:171], v175 offset:32
	v_exp_f32_e32 v98, v98
	v_exp_f32_e32 v99, v99
	v_exp_f32_e32 v100, v100
	v_mfma_f32_32x32x16_bf16 v[32:47], v[226:229], v[184:187], v[32:47]
	ds_read_b128 v[226:229], v174 offset:49216
	v_exp_f32_e32 v101, v101
	v_exp_f32_e32 v102, v102
	v_exp_f32_e32 v103, v103
	v_mfma_f32_32x32x16_bf16 v[0:15], v[234:237], v[184:187], v[0:15]
	ds_read_b128 v[234:237], v174 offset:53824
	v_exp_f32_e32 v104, v104
	v_exp_f32_e32 v105, v105
	v_exp_f32_e32 v106, v106
	v_mfma_f32_32x32x16_bf16 v[32:47], v[230:233], v[188:191], v[32:47]
	ds_read_b128 v[230:233], v174 offset:49248
	v_exp_f32_e32 v107, v107
	v_exp_f32_e32 v108, v108
	v_exp_f32_e32 v109, v109
	v_mfma_f32_32x32x16_bf16 v[0:15], v[238:241], v[188:191], v[0:15]
	ds_read_b128 v[238:241], v174 offset:53856
	v_exp_f32_e32 v110, v110
	v_exp_f32_e32 v111, v111
	v_pk_add_f32 v[200:201], v[96:97], v[200:201]
	v_cvt_pk_bf16_f32 v176, v96, v97
	v_pk_add_f32 v[200:201], v[98:99], v[200:201]
	v_cvt_pk_bf16_f32 v177, v98, v99
	v_pk_add_f32 v[200:201], v[100:101], v[200:201]
	v_cvt_pk_bf16_f32 v178, v100, v101
	v_pk_add_f32 v[200:201], v[102:103], v[200:201]
	v_cvt_pk_bf16_f32 v179, v102, v103
	v_pk_add_f32 v[200:201], v[104:105], v[200:201]
	v_cvt_pk_bf16_f32 v180, v104, v105
	v_pk_add_f32 v[200:201], v[106:107], v[200:201]
	v_cvt_pk_bf16_f32 v181, v106, v107
	v_pk_add_f32 v[200:201], v[108:109], v[200:201]
	v_cvt_pk_bf16_f32 v182, v108, v109
	v_pk_add_f32 v[200:201], v[110:111], v[200:201]
	v_cvt_pk_bf16_f32 v183, v110, v111
	s_waitcnt lgkmcnt(5)
	v_mfma_f32_32x32x16_bf16 v[96:111], v[164:167], v[130:133], v[64:79]
	v_exp_f32_e32 v112, v112
	v_exp_f32_e32 v113, v113
	s_waitcnt lgkmcnt(4)
	v_mfma_f32_32x32x16_bf16 v[96:111], v[168:171], v[134:137], v[96:111]
	ds_read_b128 v[164:167], v175 offset:5120
	ds_read_b128 v[168:171], v175 offset:5152
	v_exp_f32_e32 v114, v114
	v_exp_f32_e32 v115, v115
	v_exp_f32_e32 v116, v116
	s_waitcnt lgkmcnt(5)
	v_mfma_f32_32x32x16_bf16 v[48:63], v[226:229], v[176:179], v[48:63]
	v_exp_f32_e32 v117, v117
	v_exp_f32_e32 v118, v118
	v_exp_f32_e32 v119, v119
	s_waitcnt lgkmcnt(4)
	v_mfma_f32_32x32x16_bf16 v[16:31], v[234:237], v[176:179], v[16:31]
	v_exp_f32_e32 v120, v120
	v_exp_f32_e32 v121, v121
	v_exp_f32_e32 v122, v122
	s_waitcnt lgkmcnt(3)
	v_mfma_f32_32x32x16_bf16 v[48:63], v[230:233], v[180:183], v[48:63]
	v_exp_f32_e32 v123, v123
	v_exp_f32_e32 v124, v124
	v_exp_f32_e32 v125, v125
	s_waitcnt lgkmcnt(2)
	v_mfma_f32_32x32x16_bf16 v[16:31], v[238:241], v[180:183], v[16:31]
	s_waitcnt vmcnt(1)
	ds_write_b128 v155, v[146:149] offset:19456
	s_waitcnt vmcnt(0)
	ds_write_b128 v157, v[150:153] offset:29696
	v_exp_f32_e32 v126, v126
	v_exp_f32_e32 v127, v127
	v_pk_add_f32 v[202:203], v[112:113], v[202:203]
	v_cvt_pk_bf16_f32 v184, v112, v113
	v_pk_add_f32 v[202:203], v[114:115], v[202:203]
	v_cvt_pk_bf16_f32 v185, v114, v115
	v_pk_add_f32 v[202:203], v[116:117], v[202:203]
	v_cvt_pk_bf16_f32 v186, v116, v117
	v_pk_add_f32 v[202:203], v[118:119], v[202:203]
	v_cvt_pk_bf16_f32 v187, v118, v119
	v_pk_add_f32 v[202:203], v[120:121], v[202:203]
	v_cvt_pk_bf16_f32 v188, v120, v121
	v_pk_add_f32 v[202:203], v[122:123], v[202:203]
	v_cvt_pk_bf16_f32 v189, v122, v123
	v_pk_add_f32 v[202:203], v[124:125], v[202:203]
	v_cvt_pk_bf16_f32 v190, v124, v125
	v_pk_add_f32 v[202:203], v[126:127], v[202:203]
	v_cvt_pk_bf16_f32 v191, v126, v127
	s_add_i32 s2, s2, 1
	s_cmp_lg_u32 s2, 44
	s_cbranch_scc1 .Lat_loop
	v_mfma_f32_32x32x16_bf16 v[32:47], v[226:229], v[184:187], v[32:47]
	v_mfma_f32_32x32x16_bf16 v[0:15], v[234:237], v[184:187], v[0:15]
	v_mfma_f32_32x32x16_bf16 v[32:47], v[230:233], v[188:191], v[32:47]
	v_mfma_f32_32x32x16_bf16 v[0:15], v[238:241], v[188:191], v[0:15]
	s_waitcnt lgkmcnt(0)
	v_add_f32_e32 v158, v200, v201
	v_add_f32_e32 v159, v202, v203
	s_branch .LBB0_604

.LBB0_721:
	v_add_u32_e32 v53, s7, v51
	v_lshlrev_b32_e32 v128, 1, v50
	v_mov_b32_e32 v64, 0
	v_mov_b32_e32 v65, 0
	v_mov_b32_e32 v66, 0
	v_mov_b32_e32 v67, 0
	v_add_u32_e32 v62, 30, v53
	v_cmp_gt_u32_e32 vcc, s6, v62
	s_and_saveexec_b64 s[4:5], vcc
	s_cbranch_execz .Lcv2_0
	v_add3_u32 v64, s45, v51, 30
	s_waitcnt lgkmcnt(0)
	v_mad_i64_i32 v[64:65], s[46:47], v64, s86, v[48:49]
	v_lshl_add_u64 v[64:65], v[64:65], 0, v[128:129]
	v_add_co_u32_e32 v64, vcc, 0x3195000, v64
	s_nop 1
	v_addc_co_u32_e32 v65, vcc, 0, v65, vcc
	global_load_dwordx4 v[64:67], v[64:65], off offset:1600
.Lcv2_0:
	s_or_b64 exec, exec, s[4:5]
	v_mov_b32_e32 v68, 0
	v_mov_b32_e32 v69, 0
	v_mov_b32_e32 v70, 0
	v_mov_b32_e32 v71, 0
	v_add_u32_e32 v62, 31, v53
	v_cmp_gt_u32_e32 vcc, s6, v62
	s_and_saveexec_b64 s[4:5], vcc
	s_cbranch_execz .Lcv2_1
	v_add3_u32 v68, s45, v51, 31
	s_waitcnt lgkmcnt(0)
	v_mad_i64_i32 v[68:69], s[46:47], v68, s86, v[48:49]
	v_lshl_add_u64 v[68:69], v[68:69], 0, v[128:129]
	v_add_co_u32_e32 v68, vcc, 0x3195000, v68
	s_nop 1
	v_addc_co_u32_e32 v69, vcc, 0, v69, vcc
	global_load_dwordx4 v[68:71], v[68:69], off offset:1600
.Lcv2_1:
	s_or_b64 exec, exec, s[4:5]
	v_mov_b32_e32 v72, 0
	v_mov_b32_e32 v73, 0
	v_mov_b32_e32 v74, 0
	v_mov_b32_e32 v75, 0
	v_add_u32_e32 v62, 32, v53
	v_cmp_gt_u32_e32 vcc, s6, v62
	s_and_saveexec_b64 s[4:5], vcc
	s_cbranch_execz .Lcv2_2
	v_add3_u32 v72, s45, v51, 32
	s_waitcnt lgkmcnt(0)
	v_mad_i64_i32 v[72:73], s[46:47], v72, s86, v[48:49]
	v_lshl_add_u64 v[72:73], v[72:73], 0, v[128:129]
	v_add_co_u32_e32 v72, vcc, 0x3195000, v72
	s_nop 1
	v_addc_co_u32_e32 v73, vcc, 0, v73, vcc
	global_load_dwordx4 v[72:75], v[72:73], off offset:1600
.Lcv2_2:
	s_or_b64 exec, exec, s[4:5]
	v_mov_b32_e32 v76, 0
	v_mov_b32_e32 v77, 0
	v_mov_b32_e32 v78, 0
	v_mov_b32_e32 v79, 0
	v_add_u32_e32 v62, 33, v53
	v_cmp_gt_u32_e32 vcc, s6, v62
	s_and_saveexec_b64 s[4:5], vcc
	s_cbranch_execz .Lcv2_3
	v_add3_u32 v76, s45, v51, 33
	s_waitcnt lgkmcnt(0)
	v_mad_i64_i32 v[76:77], s[46:47], v76, s86, v[48:49]
	v_lshl_add_u64 v[76:77], v[76:77], 0, v[128:129]
	v_add_co_u32_e32 v76, vcc, 0x3195000, v76
	s_nop 1
	v_addc_co_u32_e32 v77, vcc, 0, v77, vcc
	global_load_dwordx4 v[76:79], v[76:77], off offset:1600
.Lcv2_3:
	s_or_b64 exec, exec, s[4:5]
	v_mov_b32_e32 v80, 0
	v_mov_b32_e32 v81, 0
	v_mov_b32_e32 v82, 0
	v_mov_b32_e32 v83, 0
	v_add_u32_e32 v62, 46, v53
	v_cmp_gt_u32_e32 vcc, s6, v62
	s_and_saveexec_b64 s[4:5], vcc
	s_cbranch_execz .Lcv2_4
	v_add3_u32 v80, s45, v51, 46
	s_waitcnt lgkmcnt(1)
	v_mad_i64_i32 v[80:81], s[46:47], v80, s86, v[48:49]
	v_lshl_add_u64 v[80:81], v[80:81], 0, v[128:129]
	v_add_co_u32_e32 v80, vcc, 0x3195000, v80
	s_nop 1
	v_addc_co_u32_e32 v81, vcc, 0, v81, vcc
	global_load_dwordx4 v[80:83], v[80:81], off offset:1600
.Lcv2_4:
	s_or_b64 exec, exec, s[4:5]
	v_mov_b32_e32 v84, 0
	v_mov_b32_e32 v85, 0
	v_mov_b32_e32 v86, 0
	v_mov_b32_e32 v87, 0
	v_add_u32_e32 v62, 47, v53
	v_cmp_gt_u32_e32 vcc, s6, v62
	s_and_saveexec_b64 s[4:5], vcc
	s_cbranch_execz .Lcv2_5
	v_add3_u32 v84, s45, v51, 47
	s_waitcnt lgkmcnt(1)
	v_mad_i64_i32 v[84:85], s[46:47], v84, s86, v[48:49]
	v_lshl_add_u64 v[84:85], v[84:85], 0, v[128:129]
	v_add_co_u32_e32 v84, vcc, 0x3195000, v84
	s_nop 1
	v_addc_co_u32_e32 v85, vcc, 0, v85, vcc
	global_load_dwordx4 v[84:87], v[84:85], off offset:1600
.Lcv2_5:
	s_or_b64 exec, exec, s[4:5]
	v_mov_b32_e32 v88, 0
	v_mov_b32_e32 v89, 0
	v_mov_b32_e32 v90, 0
	v_mov_b32_e32 v91, 0
	v_add_u32_e32 v62, 48, v53
	v_cmp_gt_u32_e32 vcc, s6, v62
	s_and_saveexec_b64 s[4:5], vcc
	s_cbranch_execz .Lcv2_6
	v_add3_u32 v88, s45, v51, 48
	s_waitcnt lgkmcnt(1)
	v_mad_i64_i32 v[88:89], s[46:47], v88, s86, v[48:49]
	v_lshl_add_u64 v[88:89], v[88:89], 0, v[128:129]
	v_add_co_u32_e32 v88, vcc, 0x3195000, v88
	s_nop 1
	v_addc_co_u32_e32 v89, vcc, 0, v89, vcc
	global_load_dwordx4 v[88:91], v[88:89], off offset:1600
.Lcv2_6:
	s_or_b64 exec, exec, s[4:5]
	v_mov_b32_e32 v92, 0
	v_mov_b32_e32 v93, 0
	v_mov_b32_e32 v94, 0
	v_mov_b32_e32 v95, 0
	v_add_u32_e32 v62, 49, v53
	v_cmp_gt_u32_e32 vcc, s6, v62
	s_and_saveexec_b64 s[4:5], vcc
	s_cbranch_execz .Lcv2_7
	v_add3_u32 v53, s45, v51, 49
	s_waitcnt lgkmcnt(1)
	v_mad_i64_i32 v[92:93], s[46:47], v53, s86, v[48:49]
	v_lshl_add_u64 v[92:93], v[92:93], 0, v[128:129]
	v_add_co_u32_e32 v92, vcc, 0x3195000, v92
	s_nop 1
	v_addc_co_u32_e32 v93, vcc, 0, v93, vcc
	global_load_dwordx4 v[92:95], v[92:93], off offset:1600
.Lcv2_7:
	s_or_b64 exec, exec, s[4:5]
	s_waitcnt vmcnt(0)
	s_waitcnt vmcnt(8)
	v_mov_b64_e32 v[14:15], v[6:7]
	v_mov_b64_e32 v[12:13], v[4:5]
	v_mov_b64_e32 v[10:11], v[2:3]
	v_mov_b64_e32 v[8:9], v[0:1]
	v_mov_b32_e32 v8, v64
	v_mov_b32_e32 v9, v65
	v_mov_b32_e32 v10, v66
	v_mov_b32_e32 v11, v67
	v_lshlrev_b32_e32 v54, 16, v8
	v_and_b32_e32 v55, 0xffff0000, v8
	v_lshlrev_b32_e32 v8, 16, v9
	v_and_b32_e32 v9, 0xffff0000, v9
	v_lshlrev_b32_e32 v12, 16, v10
	v_and_b32_e32 v13, 0xffff0000, v10
	v_lshlrev_b32_e32 v10, 16, v11
	v_and_b32_e32 v11, 0xffff0000, v11
	v_pk_fma_f32 v[14:15], v[18:19], v[10:11], v[6:7]
	v_pk_fma_f32 v[12:13], v[16:17], v[12:13], v[4:5]
	v_pk_fma_f32 v[10:11], v[22:23], v[8:9], v[2:3]
	v_pk_fma_f32 v[8:9], v[20:21], v[54:55], v[0:1]
	v_mov_b32_e32 v54, v68
	v_mov_b32_e32 v55, v69
	v_mov_b32_e32 v56, v70
	v_mov_b32_e32 v57, v71
	v_lshlrev_b32_e32 v58, 16, v54
	v_and_b32_e32 v59, 0xffff0000, v54
	v_lshlrev_b32_e32 v54, 16, v55
	v_and_b32_e32 v55, 0xffff0000, v55
	v_lshlrev_b32_e32 v60, 16, v56
	v_and_b32_e32 v61, 0xffff0000, v56
	v_lshlrev_b32_e32 v56, 16, v57
	v_and_b32_e32 v57, 0xffff0000, v57
	v_pk_fma_f32 v[14:15], v[26:27], v[56:57], v[14:15]
	v_pk_fma_f32 v[12:13], v[24:25], v[60:61], v[12:13]
	v_pk_fma_f32 v[10:11], v[30:31], v[54:55], v[10:11]
	v_pk_fma_f32 v[8:9], v[28:29], v[58:59], v[8:9]
	v_mov_b32_e32 v54, v72
	v_mov_b32_e32 v55, v73
	v_mov_b32_e32 v56, v74
	v_mov_b32_e32 v57, v75
	v_lshlrev_b32_e32 v58, 16, v54
	v_and_b32_e32 v59, 0xffff0000, v54
	v_lshlrev_b32_e32 v54, 16, v55
	v_and_b32_e32 v55, 0xffff0000, v55
	v_lshlrev_b32_e32 v60, 16, v56
	v_and_b32_e32 v61, 0xffff0000, v56
	v_lshlrev_b32_e32 v56, 16, v57
	v_and_b32_e32 v57, 0xffff0000, v57
	v_pk_fma_f32 v[14:15], v[34:35], v[56:57], v[14:15]
	v_pk_fma_f32 v[12:13], v[32:33], v[60:61], v[12:13]
	v_pk_fma_f32 v[10:11], v[38:39], v[54:55], v[10:11]
	v_pk_fma_f32 v[8:9], v[36:37], v[58:59], v[8:9]
	v_mov_b32_e32 v54, v76
	v_mov_b32_e32 v55, v77
	v_mov_b32_e32 v56, v78
	v_mov_b32_e32 v57, v79
	v_lshlrev_b32_e32 v58, 16, v54
	v_and_b32_e32 v59, 0xffff0000, v54
	v_lshlrev_b32_e32 v54, 16, v55
	v_and_b32_e32 v55, 0xffff0000, v55
	v_lshlrev_b32_e32 v60, 16, v56
	v_and_b32_e32 v61, 0xffff0000, v56
	v_lshlrev_b32_e32 v56, 16, v57
	v_and_b32_e32 v57, 0xffff0000, v57
	v_pk_fma_f32 v[14:15], v[42:43], v[56:57], v[14:15]
	v_pk_fma_f32 v[12:13], v[40:41], v[60:61], v[12:13]
	v_pk_fma_f32 v[10:11], v[46:47], v[54:55], v[10:11]
	v_pk_fma_f32 v[8:9], v[44:45], v[58:59], v[8:9]
	v_cvt_pk_bf16_f32 v8, v8, v9
	v_cvt_pk_bf16_f32 v9, v10, v11
	v_cvt_pk_bf16_f32 v10, v12, v13
	v_cvt_pk_bf16_f32 v11, v14, v15
	ds_write_b128 v52, v[8:11]
	v_mov_b64_e32 v[14:15], v[6:7]
	v_mov_b64_e32 v[12:13], v[4:5]
	v_mov_b64_e32 v[10:11], v[2:3]
	v_mov_b64_e32 v[8:9], v[0:1]
	v_mov_b32_e32 v8, v80
	v_mov_b32_e32 v9, v81
	v_mov_b32_e32 v10, v82
	v_mov_b32_e32 v11, v83
	v_lshlrev_b32_e32 v54, 16, v8
	v_and_b32_e32 v55, 0xffff0000, v8
	v_lshlrev_b32_e32 v8, 16, v9
	v_and_b32_e32 v9, 0xffff0000, v9
	v_lshlrev_b32_e32 v12, 16, v10
	v_and_b32_e32 v13, 0xffff0000, v10
	v_lshlrev_b32_e32 v10, 16, v11
	v_and_b32_e32 v11, 0xffff0000, v11
	v_pk_fma_f32 v[14:15], v[18:19], v[10:11], v[6:7]
	v_pk_fma_f32 v[12:13], v[16:17], v[12:13], v[4:5]
	v_pk_fma_f32 v[10:11], v[22:23], v[8:9], v[2:3]
	v_pk_fma_f32 v[8:9], v[20:21], v[54:55], v[0:1]
	v_mov_b32_e32 v54, v84
	v_mov_b32_e32 v55, v85
	v_mov_b32_e32 v56, v86
	v_mov_b32_e32 v57, v87
	v_lshlrev_b32_e32 v58, 16, v54
	v_and_b32_e32 v59, 0xffff0000, v54
	v_lshlrev_b32_e32 v54, 16, v55
	v_and_b32_e32 v55, 0xffff0000, v55
	v_lshlrev_b32_e32 v60, 16, v56
	v_and_b32_e32 v61, 0xffff0000, v56
	v_lshlrev_b32_e32 v56, 16, v57
	v_and_b32_e32 v57, 0xffff0000, v57
	v_pk_fma_f32 v[14:15], v[26:27], v[56:57], v[14:15]
	v_pk_fma_f32 v[12:13], v[24:25], v[60:61], v[12:13]
	v_pk_fma_f32 v[10:11], v[30:31], v[54:55], v[10:11]
	v_pk_fma_f32 v[8:9], v[28:29], v[58:59], v[8:9]
	v_mov_b32_e32 v54, v88
	v_mov_b32_e32 v55, v89
	v_mov_b32_e32 v56, v90
	v_mov_b32_e32 v57, v91
	v_lshlrev_b32_e32 v58, 16, v54
	v_and_b32_e32 v59, 0xffff0000, v54
	v_lshlrev_b32_e32 v54, 16, v55
	v_and_b32_e32 v55, 0xffff0000, v55
	v_lshlrev_b32_e32 v60, 16, v56
	v_and_b32_e32 v61, 0xffff0000, v56
	v_lshlrev_b32_e32 v56, 16, v57
	v_and_b32_e32 v57, 0xffff0000, v57
	v_pk_fma_f32 v[14:15], v[34:35], v[56:57], v[14:15]
	v_pk_fma_f32 v[12:13], v[32:33], v[60:61], v[12:13]
	v_pk_fma_f32 v[10:11], v[38:39], v[54:55], v[10:11]
	v_pk_fma_f32 v[8:9], v[36:37], v[58:59], v[8:9]
	v_mov_b32_e32 v54, v92
	v_mov_b32_e32 v55, v93
	v_mov_b32_e32 v56, v94
	v_mov_b32_e32 v57, v95
	v_lshlrev_b32_e32 v58, 16, v54
	v_and_b32_e32 v59, 0xffff0000, v54
	v_lshlrev_b32_e32 v54, 16, v55
	v_and_b32_e32 v55, 0xffff0000, v55
	v_lshlrev_b32_e32 v60, 16, v56
	v_and_b32_e32 v61, 0xffff0000, v56
	v_lshlrev_b32_e32 v56, 16, v57
	v_and_b32_e32 v57, 0xffff0000, v57
	v_pk_fma_f32 v[14:15], v[42:43], v[56:57], v[14:15]
	v_pk_fma_f32 v[12:13], v[40:41], v[60:61], v[12:13]
	v_pk_fma_f32 v[10:11], v[46:47], v[54:55], v[10:11]
	v_pk_fma_f32 v[8:9], v[44:45], v[58:59], v[8:9]
	s_branch .LBB0_720

.LBB0_1060:
	v_add_u32_e32 v54, s22, v52
	v_lshlrev_b32_e32 v128, 1, v51
	v_mov_b32_e32 v68, 0
	v_mov_b32_e32 v69, 0
	v_mov_b32_e32 v70, 0
	v_mov_b32_e32 v71, 0
	v_add_u32_e32 v65, 14, v54
	v_cmp_gt_u32_e32 vcc, s21, v65
	s_and_saveexec_b64 s[6:7], vcc
	s_cbranch_execz .Lcv3_0
	v_add3_u32 v68, s23, v52, 14
	v_mad_i64_i32 v[68:69], s[34:35], v68, s86, v[48:49]
	v_lshl_add_u64 v[68:69], v[68:69], 0, v[128:129]
	v_add_co_u32_e32 v68, vcc, 0x1000, v68
	s_nop 1
	v_addc_co_u32_e32 v69, vcc, 0, v69, vcc
	global_load_dwordx4 v[68:71], v[68:69], off offset:576
.Lcv3_0:
	s_or_b64 exec, exec, s[6:7]
	v_mov_b32_e32 v72, 0
	v_mov_b32_e32 v73, 0
	v_mov_b32_e32 v74, 0
	v_mov_b32_e32 v75, 0
	v_add_u32_e32 v65, 15, v54
	v_cmp_gt_u32_e32 vcc, s21, v65
	s_and_saveexec_b64 s[6:7], vcc
	s_cbranch_execz .Lcv3_1
	v_add3_u32 v55, s23, v52, 15
	v_mad_i64_i32 v[72:73], s[34:35], v55, s86, v[48:49]
	v_lshl_add_u64 v[72:73], v[72:73], 0, v[128:129]
	v_add_co_u32_e32 v72, vcc, 0x1000, v72
	s_nop 1
	v_addc_co_u32_e32 v73, vcc, 0, v73, vcc
	global_load_dwordx4 v[72:75], v[72:73], off offset:576
.Lcv3_1:
	s_or_b64 exec, exec, s[6:7]
	v_mov_b32_e32 v76, 0
	v_mov_b32_e32 v77, 0
	v_mov_b32_e32 v78, 0
	v_mov_b32_e32 v79, 0
	v_add_u32_e32 v65, 16, v54
	v_cmp_gt_u32_e32 vcc, s21, v65
	s_and_saveexec_b64 s[6:7], vcc
	s_cbranch_execz .Lcv3_2
	v_add3_u32 v55, s23, v52, 16
	v_mad_i64_i32 v[76:77], s[34:35], v55, s86, v[48:49]
	v_lshl_add_u64 v[76:77], v[76:77], 0, v[128:129]
	v_add_co_u32_e32 v76, vcc, 0x1000, v76
	s_nop 1
	v_addc_co_u32_e32 v77, vcc, 0, v77, vcc
	global_load_dwordx4 v[76:79], v[76:77], off offset:576
.Lcv3_2:
	s_or_b64 exec, exec, s[6:7]
	v_mov_b32_e32 v80, 0
	v_mov_b32_e32 v81, 0
	v_mov_b32_e32 v82, 0
	v_mov_b32_e32 v83, 0
	v_add_u32_e32 v65, 17, v54
	v_cmp_gt_u32_e32 vcc, s21, v65
	s_and_saveexec_b64 s[6:7], vcc
	s_cbranch_execz .Lcv3_3
	v_add3_u32 v55, s23, v52, 17
	v_mad_i64_i32 v[80:81], s[34:35], v55, s86, v[48:49]
	v_lshl_add_u64 v[80:81], v[80:81], 0, v[128:129]
	v_add_co_u32_e32 v80, vcc, 0x1000, v80
	s_nop 1
	v_addc_co_u32_e32 v81, vcc, 0, v81, vcc
	global_load_dwordx4 v[80:83], v[80:81], off offset:576
.Lcv3_3:
	s_or_b64 exec, exec, s[6:7]
	v_mov_b32_e32 v84, 0
	v_mov_b32_e32 v85, 0
	v_mov_b32_e32 v86, 0
	v_mov_b32_e32 v87, 0
	v_add_u32_e32 v65, 22, v54
	v_cmp_gt_u32_e32 vcc, s21, v65
	s_and_saveexec_b64 s[6:7], vcc
	s_cbranch_execz .Lcv3_4
	v_add3_u32 v84, s23, v52, 22
	v_mad_i64_i32 v[84:85], s[34:35], v84, s86, v[48:49]
	v_lshl_add_u64 v[84:85], v[84:85], 0, v[128:129]
	v_add_co_u32_e32 v84, vcc, 0x1000, v84
	s_nop 1
	v_addc_co_u32_e32 v85, vcc, 0, v85, vcc
	global_load_dwordx4 v[84:87], v[84:85], off offset:576
.Lcv3_4:
	s_or_b64 exec, exec, s[6:7]
	v_mov_b32_e32 v88, 0
	v_mov_b32_e32 v89, 0
	v_mov_b32_e32 v90, 0
	v_mov_b32_e32 v91, 0
	v_add_u32_e32 v65, 23, v54
	v_cmp_gt_u32_e32 vcc, s21, v65
	s_and_saveexec_b64 s[6:7], vcc
	s_cbranch_execz .Lcv3_5
	v_add3_u32 v55, s23, v52, 23
	v_mad_i64_i32 v[88:89], s[34:35], v55, s86, v[48:49]
	v_lshl_add_u64 v[88:89], v[88:89], 0, v[128:129]
	v_add_co_u32_e32 v88, vcc, 0x1000, v88
	s_nop 1
	v_addc_co_u32_e32 v89, vcc, 0, v89, vcc
	global_load_dwordx4 v[88:91], v[88:89], off offset:576
.Lcv3_5:
	s_or_b64 exec, exec, s[6:7]
	v_mov_b32_e32 v92, 0
	v_mov_b32_e32 v93, 0
	v_mov_b32_e32 v94, 0
	v_mov_b32_e32 v95, 0
	v_add_u32_e32 v65, 24, v54
	v_cmp_gt_u32_e32 vcc, s21, v65
	s_and_saveexec_b64 s[6:7], vcc
	s_cbranch_execz .Lcv3_6
	v_add3_u32 v55, s23, v52, 24
	v_mad_i64_i32 v[92:93], s[34:35], v55, s86, v[48:49]
	v_lshl_add_u64 v[92:93], v[92:93], 0, v[128:129]
	v_add_co_u32_e32 v92, vcc, 0x1000, v92
	s_nop 1
	v_addc_co_u32_e32 v93, vcc, 0, v93, vcc
	global_load_dwordx4 v[92:95], v[92:93], off offset:576
.Lcv3_6:
	s_or_b64 exec, exec, s[6:7]
	v_mov_b32_e32 v96, 0
	v_mov_b32_e32 v97, 0
	v_mov_b32_e32 v98, 0
	v_mov_b32_e32 v99, 0
	v_add_u32_e32 v65, 25, v54
	v_cmp_gt_u32_e32 vcc, s21, v65
	s_and_saveexec_b64 s[6:7], vcc
	s_cbranch_execz .Lcv3_7
	v_add3_u32 v96, s23, v52, 25
	v_mad_i64_i32 v[96:97], s[34:35], v96, s86, v[48:49]
	v_lshl_add_u64 v[96:97], v[96:97], 0, v[128:129]
	v_add_co_u32_e32 v96, vcc, 0x1000, v96
	s_nop 1
	v_addc_co_u32_e32 v97, vcc, 0, v97, vcc
	global_load_dwordx4 v[96:99], v[96:97], off offset:576
.Lcv3_7:
	s_or_b64 exec, exec, s[6:7]
	s_waitcnt vmcnt(0)
	s_waitcnt vmcnt(8)
	v_mov_b64_e32 v[14:15], v[6:7]
	v_mov_b64_e32 v[12:13], v[4:5]
	v_mov_b64_e32 v[10:11], v[2:3]
	v_mov_b64_e32 v[8:9], v[0:1]
	v_mov_b32_e32 v8, v68
	v_mov_b32_e32 v9, v69
	v_mov_b32_e32 v10, v70
	v_mov_b32_e32 v11, v71
	v_lshlrev_b32_e32 v56, 16, v8
	v_and_b32_e32 v57, 0xffff0000, v8
	v_lshlrev_b32_e32 v8, 16, v9
	v_and_b32_e32 v9, 0xffff0000, v9
	v_lshlrev_b32_e32 v12, 16, v10
	v_and_b32_e32 v13, 0xffff0000, v10
	v_lshlrev_b32_e32 v10, 16, v11
	v_and_b32_e32 v11, 0xffff0000, v11
	v_pk_fma_f32 v[14:15], v[18:19], v[10:11], v[6:7]
	v_pk_fma_f32 v[12:13], v[16:17], v[12:13], v[4:5]
	v_pk_fma_f32 v[10:11], v[22:23], v[8:9], v[2:3]
	v_pk_fma_f32 v[8:9], v[20:21], v[56:57], v[0:1]
	v_mov_b32_e32 v56, v72
	v_mov_b32_e32 v57, v73
	v_mov_b32_e32 v58, v74
	v_mov_b32_e32 v59, v75
	v_lshlrev_b32_e32 v60, 16, v56
	v_and_b32_e32 v61, 0xffff0000, v56
	v_lshlrev_b32_e32 v56, 16, v57
	v_and_b32_e32 v57, 0xffff0000, v57
	v_lshlrev_b32_e32 v62, 16, v58
	v_and_b32_e32 v63, 0xffff0000, v58
	v_lshlrev_b32_e32 v58, 16, v59
	v_and_b32_e32 v59, 0xffff0000, v59
	v_pk_fma_f32 v[14:15], v[26:27], v[58:59], v[14:15]
	v_pk_fma_f32 v[12:13], v[24:25], v[62:63], v[12:13]
	v_pk_fma_f32 v[10:11], v[30:31], v[56:57], v[10:11]
	v_pk_fma_f32 v[8:9], v[28:29], v[60:61], v[8:9]
	v_mov_b32_e32 v56, v76
	v_mov_b32_e32 v57, v77
	v_mov_b32_e32 v58, v78
	v_mov_b32_e32 v59, v79
	v_lshlrev_b32_e32 v60, 16, v56
	v_and_b32_e32 v61, 0xffff0000, v56
	v_lshlrev_b32_e32 v56, 16, v57
	v_and_b32_e32 v57, 0xffff0000, v57
	v_lshlrev_b32_e32 v62, 16, v58
	v_and_b32_e32 v63, 0xffff0000, v58
	v_lshlrev_b32_e32 v58, 16, v59
	v_and_b32_e32 v59, 0xffff0000, v59
	v_pk_fma_f32 v[14:15], v[38:39], v[58:59], v[14:15]
	v_pk_fma_f32 v[12:13], v[36:37], v[62:63], v[12:13]
	v_pk_fma_f32 v[10:11], v[34:35], v[56:57], v[10:11]
	v_pk_fma_f32 v[8:9], v[32:33], v[60:61], v[8:9]
	v_mov_b32_e32 v56, v80
	v_mov_b32_e32 v57, v81
	v_mov_b32_e32 v58, v82
	v_mov_b32_e32 v59, v83
	v_lshlrev_b32_e32 v60, 16, v56
	v_and_b32_e32 v61, 0xffff0000, v56
	v_lshlrev_b32_e32 v56, 16, v57
	v_and_b32_e32 v57, 0xffff0000, v57
	v_lshlrev_b32_e32 v62, 16, v58
	v_and_b32_e32 v63, 0xffff0000, v58
	v_lshlrev_b32_e32 v58, 16, v59
	v_and_b32_e32 v59, 0xffff0000, v59
	v_pk_fma_f32 v[14:15], v[46:47], v[58:59], v[14:15]
	v_pk_fma_f32 v[12:13], v[44:45], v[62:63], v[12:13]
	v_pk_fma_f32 v[10:11], v[42:43], v[56:57], v[10:11]
	v_pk_fma_f32 v[8:9], v[40:41], v[60:61], v[8:9]
	v_mul_f32_e32 v55, 0xbfb8aa3b, v8
	v_exp_f32_e32 v55, v55
	s_nop 0
	v_add_f32_e32 v55, 1.0, v55
	v_rcp_f32_e32 v56, v55
	v_mul_f32_e32 v55, 0xbfb8aa3b, v9
	v_exp_f32_e32 v55, v55
	s_nop 0
	v_add_f32_e32 v55, 1.0, v55
	v_rcp_f32_e32 v57, v55
	s_nop 0
	v_pk_mul_f32 v[8:9], v[8:9], v[56:57]
	s_nop 0
	v_cvt_pk_bf16_f32 v8, v8, v9
	v_mul_f32_e32 v9, 0xbfb8aa3b, v10
	v_exp_f32_e32 v9, v9
	s_nop 0
	v_add_f32_e32 v9, 1.0, v9
	v_rcp_f32_e32 v56, v9
	v_mul_f32_e32 v9, 0xbfb8aa3b, v11
	v_exp_f32_e32 v9, v9
	s_nop 0
	v_add_f32_e32 v9, 1.0, v9
	v_rcp_f32_e32 v57, v9
	s_nop 0
	v_pk_mul_f32 v[10:11], v[10:11], v[56:57]
	s_nop 0
	v_cvt_pk_bf16_f32 v9, v10, v11
	v_mul_f32_e32 v10, 0xbfb8aa3b, v12
	v_mul_f32_e32 v11, 0xbfb8aa3b, v13
	v_exp_f32_e32 v10, v10
	v_exp_f32_e32 v11, v11
	v_add_f32_e32 v10, 1.0, v10
	v_add_f32_e32 v11, 1.0, v11
	v_rcp_f32_e32 v10, v10
	v_rcp_f32_e32 v11, v11
	s_nop 0
	v_pk_mul_f32 v[10:11], v[12:13], v[10:11]
	s_nop 0
	v_cvt_pk_bf16_f32 v10, v10, v11
	v_mul_f32_e32 v11, 0xbfb8aa3b, v14
	v_exp_f32_e32 v11, v11
	s_nop 0
	v_add_f32_e32 v11, 1.0, v11
	v_rcp_f32_e32 v12, v11
	v_mul_f32_e32 v11, 0xbfb8aa3b, v15
	v_exp_f32_e32 v11, v11
	s_nop 0
	v_add_f32_e32 v11, 1.0, v11
	v_rcp_f32_e32 v13, v11
	s_nop 0
	v_pk_mul_f32 v[12:13], v[14:15], v[12:13]
	s_nop 0
	v_cvt_pk_bf16_f32 v11, v12, v13
	ds_write_b128 v53, v[8:11]
	v_mov_b64_e32 v[14:15], v[6:7]
	v_mov_b64_e32 v[12:13], v[4:5]
	v_mov_b64_e32 v[10:11], v[2:3]
	v_mov_b64_e32 v[8:9], v[0:1]
	v_mov_b32_e32 v8, v84
	v_mov_b32_e32 v9, v85
	v_mov_b32_e32 v10, v86
	v_mov_b32_e32 v11, v87
	v_lshlrev_b32_e32 v56, 16, v8
	v_and_b32_e32 v57, 0xffff0000, v8
	v_lshlrev_b32_e32 v8, 16, v9
	v_and_b32_e32 v9, 0xffff0000, v9
	v_lshlrev_b32_e32 v12, 16, v10
	v_and_b32_e32 v13, 0xffff0000, v10
	v_lshlrev_b32_e32 v10, 16, v11
	v_and_b32_e32 v11, 0xffff0000, v11
	v_pk_fma_f32 v[14:15], v[18:19], v[10:11], v[6:7]
	v_pk_fma_f32 v[12:13], v[16:17], v[12:13], v[4:5]
	v_pk_fma_f32 v[10:11], v[22:23], v[8:9], v[2:3]
	v_pk_fma_f32 v[8:9], v[20:21], v[56:57], v[0:1]
	v_mov_b32_e32 v56, v88
	v_mov_b32_e32 v57, v89
	v_mov_b32_e32 v58, v90
	v_mov_b32_e32 v59, v91
	v_lshlrev_b32_e32 v60, 16, v56
	v_and_b32_e32 v61, 0xffff0000, v56
	v_lshlrev_b32_e32 v56, 16, v57
	v_and_b32_e32 v57, 0xffff0000, v57
	v_lshlrev_b32_e32 v62, 16, v58
	v_and_b32_e32 v63, 0xffff0000, v58
	v_lshlrev_b32_e32 v58, 16, v59
	v_and_b32_e32 v59, 0xffff0000, v59
	v_pk_fma_f32 v[14:15], v[26:27], v[58:59], v[14:15]
	v_pk_fma_f32 v[12:13], v[24:25], v[62:63], v[12:13]
	v_pk_fma_f32 v[10:11], v[30:31], v[56:57], v[10:11]
	v_pk_fma_f32 v[8:9], v[28:29], v[60:61], v[8:9]
	v_mov_b32_e32 v56, v92
	v_mov_b32_e32 v57, v93
	v_mov_b32_e32 v58, v94
	v_mov_b32_e32 v59, v95
	v_lshlrev_b32_e32 v60, 16, v56
	v_and_b32_e32 v61, 0xffff0000, v56
	v_lshlrev_b32_e32 v56, 16, v57
	v_and_b32_e32 v57, 0xffff0000, v57
	v_lshlrev_b32_e32 v62, 16, v58
	v_and_b32_e32 v63, 0xffff0000, v58
	v_lshlrev_b32_e32 v58, 16, v59
	v_and_b32_e32 v59, 0xffff0000, v59
	v_pk_fma_f32 v[14:15], v[38:39], v[58:59], v[14:15]
	v_pk_fma_f32 v[12:13], v[36:37], v[62:63], v[12:13]
	v_pk_fma_f32 v[10:11], v[34:35], v[56:57], v[10:11]
	v_pk_fma_f32 v[8:9], v[32:33], v[60:61], v[8:9]
	v_mov_b32_e32 v54, v96
	v_mov_b32_e32 v55, v97
	v_mov_b32_e32 v56, v98
	v_mov_b32_e32 v57, v99
	v_lshlrev_b32_e32 v58, 16, v54
	v_and_b32_e32 v59, 0xffff0000, v54
	v_lshlrev_b32_e32 v54, 16, v55
	v_and_b32_e32 v55, 0xffff0000, v55
	v_lshlrev_b32_e32 v60, 16, v56
	v_and_b32_e32 v61, 0xffff0000, v56
	v_lshlrev_b32_e32 v56, 16, v57
	v_and_b32_e32 v57, 0xffff0000, v57
	v_pk_fma_f32 v[14:15], v[46:47], v[56:57], v[14:15]
	v_pk_fma_f32 v[12:13], v[44:45], v[60:61], v[12:13]
	v_pk_fma_f32 v[10:11], v[42:43], v[54:55], v[10:11]
	v_pk_fma_f32 v[8:9], v[40:41], v[58:59], v[8:9]
	s_branch .LBB0_1059
